# attention restructured: halves alternate exclusive 32-MFMA bursts (QK then PV) and softmax phases, prio raised only while bursting, single P set
# speedup vs baseline: 1.0770x; 1.0231x over previous
.LBB0_237:
	v_mov_b64_e32 v[30:31], v[14:15]
	v_mov_b64_e32 v[28:29], v[12:13]
	v_mov_b64_e32 v[26:27], v[10:11]
	v_mov_b64_e32 v[24:25], v[8:9]
	v_mov_b64_e32 v[22:23], v[6:7]
	v_mov_b64_e32 v[20:21], v[4:5]
	v_mov_b64_e32 v[18:19], v[2:3]
	v_mov_b64_e32 v[16:17], v[0:1]
	global_load_dwordx2 v[64:65], v[184:185], off
	global_load_dwordx4 v[68:71], v[182:183], off offset:448
	global_load_dwordx4 v[72:75], v[182:183], off offset:464
	global_load_dwordx4 v[20:23], v[182:183], off offset:320
	global_load_dwordx4 v[16:19], v[182:183], off offset:336
	s_lshl_b32 s0, s95, 8
	s_and_b32 s96, s0, 0x3f00
	s_mul_i32 s0, s96, 0x2400
	s_add_u32 s4, s57, s0
	s_addc_u32 s5, s59, 0
	s_lshl_b32 s0, s95, 1
	s_and_b32 s66, s0, 0xffffff80
	s_ashr_i32 s67, s66, 31
	s_lshl_b64 s[0:1], s[66:67], 1
	s_add_u32 s0, s4, s0
	s_addc_u32 s1, s5, s1
	s_ashr_i32 s4, s95, 1
	s_and_b32 s4, s4, 0xffffff80
	s_ashr_i32 s5, s4, 31
	s_lshl_b64 s[68:69], s[4:5], 1
	s_add_u32 s72, s75, s68
	s_addc_u32 s73, s76, s69
	s_add_u32 s70, s77, s68
	v_readfirstlane_b32 s97, v177
	s_addc_u32 s71, s78, s69
	s_lshr_b32 s33, s97, 6
	s_lshl_b32 s8, s33, 5
	v_or_b32_e32 v26, s8, v178
	v_mov_b64_e32 v[24:25], s[0:1]
	s_movk_i32 s0, 0x2400
	v_mad_u64_u32 v[24:25], s[0:1], v26, s0, v[24:25]
	v_lshl_add_u64 v[66:67], v[24:25], 0, v[188:189]
	v_cmp_lt_i32_e64 s[0:1], v212, v211
	global_load_dwordx4 v[94:97], v[66:67], off offset:224
	global_load_dwordx4 v[98:101], v[66:67], off offset:160
	v_cndmask_b32_e64 v52, v210, v212, s[0:1]
	v_cmp_lt_i32_e64 s[0:1], v213, v211
	global_load_dwordx4 v[44:47], v[182:183], off
	global_load_dwordx4 v[40:43], v[182:183], off offset:16
	global_load_dwordx4 v[36:39], v[182:183], off offset:64
	global_load_dwordx4 v[32:35], v[182:183], off offset:80
	global_load_dwordx4 v[104:107], v[182:183], off offset:384
	global_load_dwordx4 v[122:125], v[182:183], off offset:400
	global_load_dwordx4 v[126:129], v[66:67], off offset:192
	global_load_dwordx4 v[136:139], v[66:67], off offset:128
	global_load_dwordx4 v[28:31], v[182:183], off offset:256
	global_load_dwordx4 v[24:27], v[182:183], off offset:272
	global_load_dwordx4 v[48:51], v[182:183], off offset:128
	global_load_dwordx4 v[60:63], v[182:183], off offset:144
	global_load_dwordx4 v[140:143], v[182:183], off offset:192
	global_load_dwordx4 v[144:147], v[182:183], off offset:208
	v_cndmask_b32_e64 v53, v210, v213, s[0:1]
	v_cmp_lt_i32_e64 s[0:1], v214, v211
	v_lshlrev_b32_e32 v76, 2, v52
	v_lshlrev_b32_e32 v77, 2, v53
	v_cndmask_b32_e64 v54, v210, v214, s[0:1]
	v_cmp_lt_i32_e64 s[0:1], v215, v211
	v_lshlrev_b32_e32 v78, 2, v54
	v_or_b32_e32 v134, s96, v178
	v_cndmask_b32_e64 v55, v210, v215, s[0:1]
	v_cmp_lt_i32_e64 s[0:1], v216, v211
	v_lshlrev_b32_e32 v90, 2, v55
	s_mov_b32 s4, 0x7fffffc0
	v_cndmask_b32_e64 v56, v210, v216, s[0:1]
	v_cmp_lt_i32_e64 s[0:1], v217, v211
	v_lshlrev_b32_e32 v102, 2, v56
	v_mov_b32_e32 v195, v181
	v_cndmask_b32_e64 v57, v210, v217, s[0:1]
	v_lshlrev_b32_e32 v108, 2, v57
	global_load_dwordx4 v[52:55], v[66:67], off
	global_load_dwordx4 v[148:151], v[66:67], off offset:32
	global_load_dwordx4 v[56:59], v[66:67], off offset:64
	global_load_dwordx4 v[152:155], v[66:67], off offset:96
	s_mov_b32 s0, 0x800000
	v_mov_b32_e32 v218, v181
	s_waitcnt vmcnt(24)
	v_max_f32_e64 v66, |v65|, |v65|
	v_max_f32_e64 v67, |v64|, |v64|
	s_waitcnt vmcnt(22)
	v_mov_b32_e32 v64, v74
	v_max_f32_e32 v74, v67, v66
	s_waitcnt vmcnt(20)
	v_mov_b32_e32 v65, v18
	v_mov_b32_e32 v18, v75
	ds_bpermute_b32 v75, v76, v74
	v_mov_b32_e32 v82, v70
	v_mov_b32_e32 v66, v72
	v_mov_b32_e32 v89, v20
	v_mov_b32_e32 v88, v68
	s_waitcnt lgkmcnt(0)
	v_max_f32_e32 v70, v75, v75
	v_max_f32_e32 v70, v74, v70
	ds_bpermute_b32 v72, v77, v70
	v_mov_b32_e32 v67, v16
	v_mov_b32_e32 v16, v73
	v_mov_b32_e32 v83, v22
	v_mov_b32_e32 v22, v71
	s_waitcnt lgkmcnt(0)
	v_max_f32_e32 v20, v72, v72
	v_max_f32_e32 v20, v70, v20
	ds_bpermute_b32 v68, v78, v20
	s_waitcnt vmcnt(17)
	v_mov_b32_e32 v169, v46
	s_waitcnt lgkmcnt(0)
	v_max_f32_e32 v68, v68, v68
	v_max_f32_e32 v20, v20, v68
	ds_bpermute_b32 v68, v90, v20
	s_waitcnt vmcnt(16)
	v_mov_b32_e32 v167, v40
	s_waitcnt vmcnt(15)
	v_mov_b32_e32 v163, v36
	s_waitcnt vmcnt(11)
	v_and_b32_e32 v114, 0xffff0000, v129
	v_and_b32_e32 v118, 0xffff0000, v128
	s_waitcnt lgkmcnt(0)
	v_max_f32_e32 v68, v68, v68
	v_max_f32_e32 v20, v20, v68
	ds_bpermute_b32 v68, v102, v20
	v_and_b32_e32 v78, 0xffff0000, v97
	v_and_b32_e32 v84, 0xffff0000, v96
	v_lshlrev_b32_e32 v80, 16, v97
	v_lshlrev_b32_e32 v86, 16, v96
	s_waitcnt lgkmcnt(0)
	v_max_f32_e32 v68, v68, v68
	v_max_f32_e32 v20, v20, v68
	ds_bpermute_b32 v68, v108, v20
	v_mov_b32_e32 v72, v78
	v_mov_b32_e32 v73, v84
	v_and_b32_e32 v90, 0xffff0000, v95
	v_mov_b32_e32 v70, v80
	v_mov_b32_e32 v71, v86
	v_pk_mul_f32 v[72:73], v[72:73], v[72:73]
	v_and_b32_e32 v108, 0xffff0000, v94
	v_lshlrev_b32_e32 v92, 16, v95
	v_lshlrev_b32_e32 v102, 16, v94
	v_pk_fma_f32 v[96:97], v[70:71], v[70:71], v[72:73]
	v_mov_b32_e32 v72, v90
	v_mov_b32_e32 v73, v108
	s_waitcnt lgkmcnt(0)
	v_max_f32_e32 v68, v68, v68
	v_mov_b32_e32 v70, v92
	v_mov_b32_e32 v71, v102
	v_pk_mul_f32 v[72:73], v[72:73], v[72:73]
	v_max_f32_e32 v135, v20, v68
	v_pk_fma_f32 v[94:95], v[70:71], v[70:71], v[72:73]
	v_lshlrev_b32_e32 v112, 16, v129
	v_lshlrev_b32_e32 v68, 16, v128
	v_mov_b32_e32 v72, v114
	v_mov_b32_e32 v73, v118
	v_mov_b32_e32 v70, v112
	v_mov_b32_e32 v71, v68
	v_pk_mul_f32 v[72:73], v[72:73], v[72:73]
	s_waitcnt vmcnt(10)
	v_and_b32_e32 v131, 0xffff0000, v137
	v_and_b32_e32 v130, 0xffff0000, v127
	s_waitcnt vmcnt(6)
	v_mov_b32_e32 v40, v61
	s_waitcnt vmcnt(3)
	v_lshlrev_b32_e32 v61, 16, v53
	v_and_b32_e32 v171, 0xffff0000, v53
	s_waitcnt vmcnt(1)
	v_and_b32_e32 v170, 0xffff0000, v57
	v_lshlrev_b32_e32 v173, 16, v52
	v_and_b32_e32 v53, 0xffff0000, v52
	v_and_b32_e32 v52, 0xffff0000, v56
	v_lshlrev_b32_e32 v93, 16, v99
	v_and_b32_e32 v91, 0xffff0000, v99
	v_lshlrev_b32_e32 v103, 16, v98
	v_and_b32_e32 v109, 0xffff0000, v98
	v_pk_fma_f32 v[98:99], v[70:71], v[70:71], v[72:73]
	v_lshlrev_b32_e32 v71, 16, v137
	v_lshlrev_b32_e32 v70, 16, v127
	v_pk_mul_f32 v[74:75], v[130:131], v[130:131]
	v_mov_b32_e32 v158, v144
	s_waitcnt vmcnt(0)
	v_lshlrev_b32_e32 v144, 16, v153
	v_and_b32_e32 v160, 0xffff0000, v153
	v_mov_b32_e32 v36, v141
	v_lshlrev_b32_e32 v141, 16, v55
	v_mov_b32_e32 v153, v42
	v_and_b32_e32 v165, 0xffff0000, v55
	v_mov_b32_e32 v42, v63
	v_lshlrev_b32_e32 v63, 16, v54
	v_mov_b32_e32 v166, v60
	v_and_b32_e32 v55, 0xffff0000, v54
	v_and_b32_e32 v54, 0xffff0000, v58
	v_lshlrev_b32_e32 v60, 16, v57
	v_pk_mul_f32 v[128:129], v[170:171], v[170:171]
	v_lshlrev_b32_e32 v172, 16, v56
	v_pk_mul_f32 v[56:57], v[52:53], v[52:53]
	v_lshlrev_b32_e32 v81, 16, v101
	v_and_b32_e32 v79, 0xffff0000, v101
	v_lshlrev_b32_e32 v87, 16, v100
	v_and_b32_e32 v85, 0xffff0000, v100
	v_mov_b32_e32 v20, v69
	v_lshlrev_b32_e32 v113, 16, v139
	v_and_b32_e32 v115, 0xffff0000, v139
	v_lshlrev_b32_e32 v69, 16, v138
	v_and_b32_e32 v119, 0xffff0000, v138
	v_pk_fma_f32 v[100:101], v[70:71], v[70:71], v[74:75]
	v_lshlrev_b32_e32 v75, 16, v136
	v_and_b32_e32 v133, 0xffff0000, v136
	v_lshlrev_b32_e32 v137, 16, v151
	v_lshlrev_b32_e32 v136, 16, v155
	v_mov_b32_e32 v138, v146
	v_mov_b32_e32 v139, v34
	v_and_b32_e32 v157, 0xffff0000, v151
	v_and_b32_e32 v156, 0xffff0000, v155
	v_mov_b32_e32 v34, v147
	v_lshlrev_b32_e32 v147, 16, v150
	v_lshlrev_b32_e32 v146, 16, v154
	v_mov_b32_e32 v159, v32
	v_and_b32_e32 v151, 0xffff0000, v150
	v_and_b32_e32 v150, 0xffff0000, v154
	v_mov_b32_e32 v32, v145
	v_lshlrev_b32_e32 v145, 16, v149
	v_mov_b32_e32 v154, v142
	v_mov_b32_e32 v155, v38
	v_and_b32_e32 v161, 0xffff0000, v149
	v_mov_b32_e32 v38, v143
	v_lshlrev_b32_e32 v143, 16, v148
	v_lshlrev_b32_e32 v142, 16, v152
	v_mov_b32_e32 v162, v140
	v_and_b32_e32 v149, 0xffff0000, v148
	v_and_b32_e32 v148, 0xffff0000, v152
	v_lshlrev_b32_e32 v140, 16, v59
	v_mov_b32_e32 v152, v62
	v_and_b32_e32 v164, 0xffff0000, v59
	v_lshlrev_b32_e32 v62, 16, v58
	v_pk_mul_f32 v[58:59], v[54:55], v[54:55]
	v_pk_fma_f32 v[128:129], v[60:61], v[60:61], v[128:129]
	v_pk_fma_f32 v[56:57], v[172:173], v[172:173], v[56:57]
	v_lshlrev_b32_e32 v74, 16, v126
	v_and_b32_e32 v132, 0xffff0000, v126
	v_pk_mul_f32 v[126:127], v[164:165], v[164:165]
	v_pk_fma_f32 v[58:59], v[62:63], v[62:63], v[58:59]
	v_add_f32_e32 v46, v57, v129
	v_mov_b32_e32 v116, v124
	v_mov_b32_e32 v117, v26
	v_mov_b32_e32 v26, v125
	v_pk_mul_f32 v[124:125], v[148:149], v[148:149]
	v_pk_fma_f32 v[126:127], v[140:141], v[140:141], v[126:127]
	v_add_f32_e32 v46, v59, v46
	v_mov_b32_e32 v120, v122
	v_mov_b32_e32 v121, v24
	v_mov_b32_e32 v24, v123
	v_pk_mul_f32 v[122:123], v[160:161], v[160:161]
	v_pk_fma_f32 v[124:125], v[142:143], v[142:143], v[124:125]
	v_add_f32_e32 v46, v127, v46
	v_pk_mul_f32 v[110:111], v[150:151], v[150:151]
	v_pk_fma_f32 v[122:123], v[144:145], v[144:145], v[122:123]
	v_add_f32_e32 v46, v125, v46
	v_mov_b32_e32 v76, v104
	v_mov_b32_e32 v77, v28
	v_mov_b32_e32 v28, v105
	v_pk_mul_f32 v[104:105], v[156:157], v[156:157]
	v_pk_fma_f32 v[110:111], v[146:147], v[146:147], v[110:111]
	v_add_f32_e32 v46, v123, v46
	v_pk_fma_f32 v[104:105], v[136:137], v[136:137], v[104:105]
	v_add_f32_e32 v46, v111, v46
	v_add_f32_e32 v46, v105, v46
	v_pk_add_f32 v[56:57], v[56:57], v[46:47] op_sel_hi:[1,0]
	v_mov_b32_e32 v72, v106
	v_pk_add_f32 v[56:57], v[128:129], v[56:57]
	v_mov_b32_e32 v73, v30
	v_pk_add_f32 v[56:57], v[58:59], v[56:57]
	v_mov_b32_e32 v30, v107
	v_pk_add_f32 v[56:57], v[126:127], v[56:57]
	v_pk_mul_f32 v[106:107], v[132:133], v[132:133]
	v_pk_add_f32 v[56:57], v[124:125], v[56:57]
	v_pk_fma_f32 v[106:107], v[74:75], v[74:75], v[106:107]
	v_pk_add_f32 v[56:57], v[122:123], v[56:57]
	v_mul_f32_e32 v46, v69, v69
	v_pk_add_f32 v[56:57], v[110:111], v[56:57]
	v_fmac_f32_e32 v46, v119, v119
	v_pk_add_f32 v[56:57], v[104:105], v[56:57]
	v_mov_b32_e32 v168, v50
	v_pk_add_f32 v[56:57], v[106:107], v[56:57] op_sel:[1,0] op_sel_hi:[0,1]
	v_pk_add_f32 v[56:57], v[100:101], v[56:57] op_sel:[1,0] op_sel_hi:[0,1]
	v_pk_add_f32 v[56:57], v[46:47], v[56:57] op_sel_hi:[0,1]
	v_mul_f32_e32 v46, v113, v113
	v_fmac_f32_e32 v46, v115, v115
	v_pk_add_f32 v[56:57], v[46:47], v[56:57] op_sel_hi:[0,1]
	v_mul_f32_e32 v46, v103, v103
	v_fmac_f32_e32 v46, v109, v109
	v_pk_add_f32 v[56:57], v[46:47], v[56:57] op_sel_hi:[0,1]
	v_mul_f32_e32 v46, v93, v93
	v_fmac_f32_e32 v46, v91, v91
	v_pk_add_f32 v[56:57], v[46:47], v[56:57] op_sel_hi:[0,1]
	v_mul_f32_e32 v46, v87, v87
	v_fmac_f32_e32 v46, v85, v85
	v_pk_add_f32 v[56:57], v[46:47], v[56:57] op_sel_hi:[0,1]
	v_mul_f32_e32 v46, v81, v81
	v_fmac_f32_e32 v46, v79, v79
	v_pk_add_f32 v[56:57], v[46:47], v[56:57] op_sel_hi:[0,1]
	v_pk_add_f32 v[56:57], v[106:107], v[56:57]
	s_nop 0
	v_pk_add_f32 v[56:57], v[100:101], v[56:57]
	s_nop 0
	v_pk_add_f32 v[56:57], v[98:99], v[56:57] op_sel:[1,0] op_sel_hi:[0,1]
	v_pk_add_f32 v[56:57], v[98:99], v[56:57]
	s_nop 0
	v_pk_add_f32 v[56:57], v[94:95], v[56:57] op_sel:[1,0] op_sel_hi:[0,1]
	v_pk_add_f32 v[56:57], v[94:95], v[56:57]
	s_nop 0
	v_pk_add_f32 v[56:57], v[96:97], v[56:57] op_sel:[1,0] op_sel_hi:[0,1]
	v_pk_add_f32 v[56:57], v[96:97], v[56:57]
	s_nop 0
	v_mov_b32_e32 v46, v56
	s_nop 1
	v_permlane32_swap_b32_e32 v56, v46
	v_add_f32_e32 v46, v56, v46
	v_fmamk_f32 v46, v46, 0x3c000000, v208
	v_mul_f32_e32 v50, 0x4b800000, v46
	v_cmp_gt_f32_e64 s[0:1], s0, v46
	s_nop 1
	v_cndmask_b32_e64 v46, v46, v50, s[0:1]
	v_rsq_f32_e32 v56, v46
	v_mov_b32_e32 v46, v51
	v_mov_b32_e32 v51, v44
	v_mov_b32_e32 v50, v48
	v_mul_f32_e32 v44, 0x45800000, v56
	v_cndmask_b32_e64 v174, v56, v44, s[0:1]
	v_pk_mul_f32 v[40:41], v[174:175], v[40:41] op_sel_hi:[0,1]
	v_pk_mul_f32 v[36:37], v[174:175], v[36:37] op_sel_hi:[0,1]
	v_pk_mul_f32 v[106:107], v[40:41], v[54:55]
	v_pk_mul_f32 v[40:41], v[174:175], v[152:153] op_sel_hi:[0,1]
	v_pk_mul_f32 v[96:97], v[36:37], v[148:149]
	v_pk_mul_f32 v[36:37], v[174:175], v[154:155] op_sel_hi:[0,1]
	v_pk_mul_f32 v[50:51], v[174:175], v[50:51] op_sel_hi:[0,1]
	v_mov_b32_e32 v44, v49
	v_pk_mul_f32 v[104:105], v[40:41], v[140:141]
	v_pk_mul_f32 v[40:41], v[174:175], v[42:43] op_sel_hi:[0,1]
	v_pk_mul_f32 v[94:95], v[36:37], v[144:145]
	v_pk_mul_f32 v[36:37], v[174:175], v[38:39] op_sel_hi:[0,1]
	v_pk_mul_f32 v[32:33], v[174:175], v[32:33] op_sel_hi:[0,1]
	v_pk_mul_f32 v[128:129], v[50:51], v[172:173]
	v_pk_mul_f32 v[44:45], v[174:175], v[44:45] op_sel_hi:[0,1]
	v_pk_mul_f32 v[100:101], v[40:41], v[164:165]
	v_pk_mul_f32 v[40:41], v[174:175], v[162:163] op_sel_hi:[0,1]
	v_pk_mul_f32 v[42:43], v[36:37], v[160:161]
	v_pk_mul_f32 v[36:37], v[174:175], v[158:159] op_sel_hi:[0,1]
	v_pk_mul_f32 v[38:39], v[32:33], v[150:151]
	v_pk_mul_f32 v[32:33], v[174:175], v[138:139] op_sel_hi:[0,1]
	v_pk_mul_f32 v[126:127], v[44:45], v[52:53]
	v_pk_mul_f32 v[44:45], v[174:175], v[168:169] op_sel_hi:[0,1]
	v_pk_mul_f32 v[98:99], v[40:41], v[142:143]
	v_pk_mul_f32 v[40:41], v[36:37], v[146:147]
	v_pk_mul_f32 v[36:37], v[32:33], v[136:137]
	v_pk_mul_f32 v[32:33], v[174:175], v[34:35] op_sel_hi:[0,1]
	v_mul_f32_e32 v34, v129, v129
	v_pk_mul_f32 v[124:125], v[44:45], v[60:61]
	v_pk_mul_f32 v[44:45], v[174:175], v[46:47] op_sel_hi:[0,1]
	v_fmac_f32_e32 v34, v127, v127
	v_pk_mul_f32 v[122:123], v[44:45], v[170:171]
	v_pk_mul_f32 v[44:45], v[174:175], v[166:167] op_sel_hi:[0,1]
	v_fmac_f32_e32 v34, v125, v125
	v_pk_mul_f32 v[110:111], v[44:45], v[62:63]
	v_fmac_f32_e32 v34, v123, v123
	v_fmac_f32_e32 v34, v111, v111
	v_fmac_f32_e32 v34, v107, v107
	v_fmac_f32_e32 v34, v105, v105
	v_fmac_f32_e32 v34, v101, v101
	v_fmac_f32_e32 v34, v99, v99
	v_fmac_f32_e32 v34, v97, v97
	v_fmac_f32_e32 v34, v95, v95
	v_fmac_f32_e32 v34, v43, v43
	v_fmac_f32_e32 v34, v41, v41
	v_fmac_f32_e32 v34, v39, v39
	v_pk_mul_f32 v[32:33], v[32:33], v[156:157]
	v_fmac_f32_e32 v34, v37, v37
	v_fmac_f32_e32 v34, v33, v33
	v_pk_fma_f32 v[34:35], v[128:129], v[128:129], v[34:35] op_sel_hi:[1,1,0]
	v_pk_mul_f32 v[44:45], v[174:175], v[76:77] op_sel_hi:[0,1]
	v_pk_fma_f32 v[34:35], v[126:127], v[126:127], v[34:35]
	v_pk_mul_f32 v[76:77], v[44:45], v[74:75]
	v_pk_fma_f32 v[34:35], v[124:125], v[124:125], v[34:35]
	v_pk_mul_f32 v[28:29], v[174:175], v[28:29] op_sel_hi:[0,1]
	v_pk_fma_f32 v[34:35], v[122:123], v[122:123], v[34:35]
	v_mul_f32_e32 v44, v77, v77
	v_pk_fma_f32 v[34:35], v[110:111], v[110:111], v[34:35]
	v_pk_mul_f32 v[74:75], v[28:29], v[132:133]
	v_pk_fma_f32 v[34:35], v[106:107], v[106:107], v[34:35]
	v_mul_f32_e32 v28, v75, v75
	v_pk_fma_f32 v[34:35], v[104:105], v[104:105], v[34:35]
	v_pk_mul_f32 v[30:31], v[174:175], v[30:31] op_sel_hi:[0,1]
	v_pk_fma_f32 v[34:35], v[100:101], v[100:101], v[34:35]
	v_pk_mul_f32 v[24:25], v[174:175], v[24:25] op_sel_hi:[0,1]
	v_pk_fma_f32 v[34:35], v[98:99], v[98:99], v[34:35]
	v_pk_mul_f32 v[62:63], v[24:25], v[118:119]
	v_pk_fma_f32 v[34:35], v[96:97], v[96:97], v[34:35]
	v_mul_f32_e32 v24, v63, v63
	v_pk_fma_f32 v[34:35], v[94:95], v[94:95], v[34:35]
	v_pk_mul_f32 v[26:27], v[174:175], v[26:27] op_sel_hi:[0,1]
	v_pk_fma_f32 v[34:35], v[42:43], v[42:43], v[34:35]
	v_pk_mul_f32 v[58:59], v[26:27], v[114:115]
	v_pk_fma_f32 v[34:35], v[40:41], v[40:41], v[34:35]
	v_mul_f32_e32 v26, v59, v59
	v_pk_fma_f32 v[34:35], v[38:39], v[38:39], v[34:35]
	v_pk_mul_f32 v[20:21], v[174:175], v[20:21] op_sel_hi:[0,1]
	v_pk_fma_f32 v[34:35], v[36:37], v[36:37], v[34:35]
	v_pk_mul_f32 v[54:55], v[20:21], v[108:109]
	v_pk_fma_f32 v[34:35], v[32:33], v[32:33], v[34:35]
	v_mul_f32_e32 v20, v55, v55
	v_pk_add_f32 v[34:35], v[44:45], v[34:35] op_sel_hi:[0,1]
	v_pk_add_f32 v[28:29], v[28:29], v[34:35] op_sel_hi:[0,1]
	v_pk_mul_f32 v[34:35], v[174:175], v[72:73] op_sel_hi:[0,1]
	v_pk_mul_f32 v[72:73], v[34:35], v[70:71]
	v_pk_mul_f32 v[70:71], v[30:31], v[130:131]
	v_mul_f32_e32 v34, v73, v73
	v_pk_add_f32 v[28:29], v[34:35], v[28:29] op_sel_hi:[0,1]
	v_mul_f32_e32 v30, v71, v71
	v_pk_add_f32 v[28:29], v[30:31], v[28:29] op_sel_hi:[0,1]
	v_pk_mul_f32 v[30:31], v[174:175], v[120:121] op_sel_hi:[0,1]
	v_pk_mul_f32 v[68:69], v[30:31], v[68:69]
	v_pk_mul_f32 v[22:23], v[174:175], v[22:23] op_sel_hi:[0,1]
	v_mul_f32_e32 v30, v69, v69
	v_pk_add_f32 v[28:29], v[30:31], v[28:29] op_sel_hi:[0,1]
	v_pk_add_f32 v[24:25], v[24:25], v[28:29] op_sel_hi:[0,1]
	v_pk_mul_f32 v[28:29], v[174:175], v[116:117] op_sel_hi:[0,1]
	v_pk_mul_f32 v[60:61], v[28:29], v[112:113]
	v_pk_mul_f32 v[50:51], v[22:23], v[90:91]
	v_mul_f32_e32 v28, v61, v61
	v_pk_add_f32 v[24:25], v[28:29], v[24:25] op_sel_hi:[0,1]
	v_pk_add_f32 v[24:25], v[26:27], v[24:25] op_sel_hi:[0,1]
	v_pk_mul_f32 v[26:27], v[174:175], v[88:89] op_sel_hi:[0,1]
	v_pk_mul_f32 v[56:57], v[26:27], v[102:103]
	v_mul_f32_e32 v22, v51, v51
	v_mul_f32_e32 v26, v57, v57
	v_pk_add_f32 v[24:25], v[26:27], v[24:25] op_sel_hi:[0,1]
	v_pk_add_f32 v[20:21], v[20:21], v[24:25] op_sel_hi:[0,1]
	v_pk_mul_f32 v[24:25], v[174:175], v[82:83] op_sel_hi:[0,1]
	v_pk_mul_f32 v[52:53], v[24:25], v[92:93]
	v_pk_mul_f32 v[16:17], v[174:175], v[16:17] op_sel_hi:[0,1]
	v_mul_f32_e32 v24, v53, v53
	v_pk_add_f32 v[20:21], v[24:25], v[20:21] op_sel_hi:[0,1]
	v_pk_add_f32 v[20:21], v[22:23], v[20:21] op_sel_hi:[0,1]
	v_pk_mul_f32 v[22:23], v[174:175], v[66:67] op_sel_hi:[0,1]
	v_pk_mul_f32 v[48:49], v[22:23], v[86:87]
	v_pk_mul_f32 v[46:47], v[16:17], v[84:85]
	v_mul_f32_e32 v22, v49, v49
	v_pk_add_f32 v[20:21], v[22:23], v[20:21] op_sel_hi:[0,1]
	v_mul_f32_e32 v16, v47, v47
	v_pk_add_f32 v[16:17], v[16:17], v[20:21] op_sel_hi:[0,1]
	v_pk_mul_f32 v[20:21], v[174:175], v[64:65] op_sel_hi:[0,1]
	v_pk_mul_f32 v[44:45], v[20:21], v[80:81]
	v_pk_mul_f32 v[18:19], v[174:175], v[18:19] op_sel_hi:[0,1]
	v_mul_f32_e32 v20, v45, v45
	v_pk_mul_f32 v[34:35], v[18:19], v[78:79]
	v_pk_add_f32 v[16:17], v[20:21], v[16:17] op_sel_hi:[0,1]
	v_mul_f32_e32 v18, v35, v35
	v_pk_add_f32 v[16:17], v[18:19], v[16:17] op_sel_hi:[0,1]
	v_pk_fma_f32 v[16:17], v[76:77], v[76:77], v[16:17]
	s_mov_b32 s0, 0xf800000
	v_pk_fma_f32 v[16:17], v[74:75], v[74:75], v[16:17]
	v_add_u32_e32 v108, s8, v134
	v_pk_fma_f32 v[16:17], v[72:73], v[72:73], v[16:17]
	v_and_or_b32 v180, v108, s4, v200
	v_pk_fma_f32 v[16:17], v[70:71], v[70:71], v[16:17]
	v_lshl_add_u64 v[102:103], v[180:181], 2, s[6:7]
	v_pk_fma_f32 v[16:17], v[68:69], v[68:69], v[16:17]
	v_lshlrev_b32_e32 v108, 6, v108
	v_pk_fma_f32 v[16:17], v[62:63], v[62:63], v[16:17]
	s_nop 0
	v_pk_fma_f32 v[16:17], v[60:61], v[60:61], v[16:17]
	s_nop 0
	v_pk_fma_f32 v[16:17], v[58:59], v[58:59], v[16:17]
	s_nop 0
	v_pk_fma_f32 v[16:17], v[56:57], v[56:57], v[16:17]
	s_nop 0
	v_pk_fma_f32 v[16:17], v[54:55], v[54:55], v[16:17]
	s_nop 0
	v_pk_fma_f32 v[16:17], v[52:53], v[52:53], v[16:17]
	s_nop 0
	v_pk_fma_f32 v[16:17], v[50:51], v[50:51], v[16:17]
	s_nop 0
	v_pk_fma_f32 v[16:17], v[48:49], v[48:49], v[16:17]
	s_nop 0
	v_pk_fma_f32 v[16:17], v[46:47], v[46:47], v[16:17]
	s_nop 0
	v_pk_fma_f32 v[16:17], v[44:45], v[44:45], v[16:17]
	s_nop 0
	v_pk_fma_f32 v[16:17], v[34:35], v[34:35], v[16:17]
	s_nop 0
	v_mov_b32_e32 v17, v16
	s_nop 1
	v_permlane32_swap_b32_e32 v16, v17
	v_add_f32_e32 v16, v16, v17
	v_mul_f32_e32 v17, 0x4f800000, v16
	v_cmp_gt_f32_e64 s[0:1], s0, v16
	s_nop 1
	v_cndmask_b32_e64 v16, v16, v17, s[0:1]
	v_sqrt_f32_e32 v17, v16
	s_nop 0
	v_add_u32_e32 v18, -1, v17
	v_fma_f32 v19, -v18, v17, v16
	v_cmp_ge_f32_e64 s[4:5], 0, v19
	v_add_u32_e32 v19, 1, v17
	s_nop 0
	v_cndmask_b32_e64 v18, v17, v18, s[4:5]
	v_fma_f32 v17, -v19, v17, v16
	v_cmp_lt_f32_e64 s[4:5], 0, v17
	s_nop 1
	v_cndmask_b32_e64 v17, v18, v19, s[4:5]
	v_mul_f32_e32 v18, 0x37800000, v17
	v_cndmask_b32_e64 v17, v17, v18, s[0:1]
	v_cmp_class_f32_e64 s[0:1], v16, v209
	s_movk_i32 s4, 0x4000
	s_nop 0
	v_cndmask_b32_e64 v16, v17, v16, s[0:1]
	v_mul_f32_e32 v16, 0x3e0293ee, v16
	v_mul_f32_e32 v16, 0xc13504f3, v16
	v_mul_f32_e32 v16, v16, v135
	v_mul_f32_e32 v16, 0x3f801062, v16
	v_max_f32_e32 v16, 0xc2700000, v16
	v_mov_b32_e32 v17, v16
	v_mov_b32_e32 v18, v16
	v_mov_b32_e32 v19, v16
	v_mov_b32_e32 v20, v16
	v_mov_b32_e32 v21, v16
	v_mov_b32_e32 v22, v16
	v_mov_b32_e32 v23, v16
	v_mov_b32_e32 v24, v16
	v_mov_b32_e32 v25, v16
	v_mov_b32_e32 v26, v16
	v_mov_b32_e32 v27, v16
	v_mov_b32_e32 v28, v16
	v_mov_b32_e32 v29, v16
	v_mov_b32_e32 v30, v16
	v_mov_b32_e32 v31, v16
	global_load_dwordx4 v[64:67], v[102:103], off
	global_load_dwordx4 v[78:81], v[102:103], off offset:16
	global_load_dwordx4 v[82:85], v[102:103], off offset:32
	global_load_dwordx4 v[86:89], v[102:103], off offset:48
	global_load_dwordx4 v[90:93], v[102:103], off offset:128
	global_load_dwordx4 v[112:115], v[102:103], off offset:144
	global_load_dwordx4 v[116:119], v[102:103], off offset:176
	global_load_dwordx4 v[130:133], v[102:103], off offset:160
	s_movk_i32 s0, 0xfc0
	v_and_or_b32 v108, v108, s0, v200
	v_lshlrev_b32_e32 v108, 2, v108
	s_lshr_b32 s0, s97, 3
	s_and_b32 s0, s0, 0x1ffffff0
	s_waitcnt vmcnt(7)
	v_pk_mul_f32 v[102:103], v[128:129], v[64:65] op_sel:[1,0] op_sel_hi:[0,1]
	v_pk_mul_f32 v[64:65], v[128:129], v[64:65]
	v_sub_f32_e32 v102, v102, v103
	v_add_f32_e32 v64, v64, v65
	v_mul_f32_e32 v120, 0x3e0293ee, v64
	v_pk_mul_f32 v[64:65], v[126:127], v[66:67] op_sel:[1,0] op_sel_hi:[0,1]
	v_sub_f32_e32 v64, v64, v65
	v_mul_f32_e32 v121, 0x3e0293ee, v64
	v_pk_mul_f32 v[64:65], v[126:127], v[66:67]
	v_mul_f32_e32 v109, 0x3e0293ee, v102
	v_add_f32_e32 v64, v64, v65
	v_mul_f32_e32 v126, 0x3e0293ee, v64
	s_waitcnt vmcnt(6)
	v_pk_mul_f32 v[64:65], v[124:125], v[78:79] op_sel:[1,0] op_sel_hi:[0,1]
	v_sub_f32_e32 v64, v64, v65
	v_mul_f32_e32 v127, 0x3e0293ee, v64
	v_pk_mul_f32 v[64:65], v[124:125], v[78:79]
	s_nop 0
	v_add_f32_e32 v64, v64, v65
	v_mul_f32_e32 v124, 0x3e0293ee, v64
	v_pk_mul_f32 v[64:65], v[122:123], v[80:81] op_sel:[1,0] op_sel_hi:[0,1]
	v_sub_f32_e32 v64, v64, v65
	v_mul_f32_e32 v125, 0x3e0293ee, v64
	v_pk_mul_f32 v[64:65], v[122:123], v[80:81]
	s_nop 0
	v_add_f32_e32 v102, v64, v65
	global_load_dwordx4 v[64:67], v108, s[6:7] offset:16
	global_load_dwordx4 v[78:81], v108, s[6:7]
	v_mul_f32_e32 v122, 0x3e0293ee, v102
	s_waitcnt vmcnt(7)
	v_pk_mul_f32 v[102:103], v[110:111], v[82:83] op_sel:[1,0] op_sel_hi:[0,1]
	v_pk_mul_f32 v[82:83], v[110:111], v[82:83]
	v_sub_f32_e32 v102, v102, v103
	v_add_f32_e32 v82, v82, v83
	v_mul_f32_e32 v110, 0x3e0293ee, v82
	v_pk_mul_f32 v[82:83], v[106:107], v[84:85] op_sel:[1,0] op_sel_hi:[0,1]
	v_sub_f32_e32 v82, v82, v83
	v_mul_f32_e32 v111, 0x3e0293ee, v82
	v_pk_mul_f32 v[82:83], v[106:107], v[84:85]
	v_mul_f32_e32 v123, 0x3e0293ee, v102
	v_add_f32_e32 v82, v82, v83
	v_mul_f32_e32 v106, 0x3e0293ee, v82
	s_waitcnt vmcnt(6)
	v_pk_mul_f32 v[82:83], v[104:105], v[86:87] op_sel:[1,0] op_sel_hi:[0,1]
	v_sub_f32_e32 v82, v82, v83
	v_mul_f32_e32 v107, 0x3e0293ee, v82
	v_pk_mul_f32 v[82:83], v[104:105], v[86:87]
	v_pk_mul_f32 v[86:87], v[100:101], v[88:89]
	v_add_f32_e32 v82, v82, v83
	v_mul_f32_e32 v128, 0x3e0293ee, v82
	v_pk_mul_f32 v[82:83], v[100:101], v[88:89] op_sel:[1,0] op_sel_hi:[0,1]
	v_sub_f32_e32 v82, v82, v83
	v_mul_f32_e32 v129, 0x3e0293ee, v82
	global_load_dwordx4 v[82:85], v108, s[6:7] offset:48
	global_load_dwordx4 v[102:105], v108, s[6:7] offset:32
	v_add_f32_e32 v86, v86, v87
	v_mul_f32_e32 v100, 0x3e0293ee, v86
	s_waitcnt vmcnt(7)
	v_pk_mul_f32 v[86:87], v[98:99], v[90:91] op_sel:[1,0] op_sel_hi:[0,1]
	v_sub_f32_e32 v86, v86, v87
	v_mul_f32_e32 v101, 0x3e0293ee, v86
	v_pk_mul_f32 v[86:87], v[98:99], v[90:91]
	s_nop 0
	v_add_f32_e32 v86, v86, v87
	v_mul_f32_e32 v98, 0x3e0293ee, v86
	v_pk_mul_f32 v[86:87], v[96:97], v[92:93] op_sel:[1,0] op_sel_hi:[0,1]
	v_sub_f32_e32 v86, v86, v87
	v_mul_f32_e32 v99, 0x3e0293ee, v86
	v_pk_mul_f32 v[86:87], v[96:97], v[92:93]
	s_nop 0
	v_add_f32_e32 v86, v86, v87
	v_mul_f32_e32 v96, 0x3e0293ee, v86
	s_waitcnt vmcnt(6)
	v_pk_mul_f32 v[86:87], v[94:95], v[112:113] op_sel:[1,0] op_sel_hi:[0,1]
	v_sub_f32_e32 v86, v86, v87
	v_mul_f32_e32 v97, 0x3e0293ee, v86
	v_pk_mul_f32 v[86:87], v[94:95], v[112:113]
	v_pk_mul_f32 v[94:95], v[42:43], v[114:115] op_sel:[1,0] op_sel_hi:[0,1]
	v_add_f32_e32 v86, v86, v87
	v_mul_f32_e32 v112, 0x3e0293ee, v86
	global_load_dwordx4 v[86:89], v108, s[6:7] offset:144
	global_load_dwordx4 v[90:93], v108, s[6:7] offset:128
	v_pk_mul_f32 v[42:43], v[42:43], v[114:115]
	v_sub_f32_e32 v94, v94, v95
	v_add_f32_e32 v42, v42, v43
	v_mul_f32_e32 v114, 0x3e0293ee, v42
	s_waitcnt vmcnt(6)
	v_pk_mul_f32 v[42:43], v[40:41], v[130:131] op_sel:[1,0] op_sel_hi:[0,1]
	v_pk_mul_f32 v[40:41], v[40:41], v[130:131]
	v_sub_f32_e32 v42, v42, v43
	v_add_f32_e32 v40, v40, v41
	v_mul_f32_e32 v130, 0x3e0293ee, v40
	v_pk_mul_f32 v[40:41], v[38:39], v[132:133] op_sel:[1,0] op_sel_hi:[0,1]
	v_pk_mul_f32 v[38:39], v[38:39], v[132:133]
	v_sub_f32_e32 v40, v40, v41
	v_add_f32_e32 v38, v38, v39
	v_mul_f32_e32 v132, 0x3e0293ee, v38
	v_pk_mul_f32 v[38:39], v[36:37], v[116:117] op_sel:[1,0] op_sel_hi:[0,1]
	v_sub_f32_e32 v38, v38, v39
	v_pk_mul_f32 v[36:37], v[36:37], v[116:117]
	v_mul_f32_e32 v113, 0x3e0293ee, v94
	v_mul_f32_e32 v115, 0x3e0293ee, v42
	v_mul_f32_e32 v131, 0x3e0293ee, v40
	v_mul_f32_e32 v133, 0x3e0293ee, v38
	v_add_f32_e32 v94, v36, v37
	global_load_dwordx4 v[36:39], v108, s[6:7] offset:176
	global_load_dwordx4 v[40:43], v108, s[6:7] offset:160
	v_mul_f32_e32 v108, 0x3e0293ee, v94
	v_pk_mul_f32 v[94:95], v[32:33], v[118:119] op_sel:[1,0] op_sel_hi:[0,1]
	v_pk_mul_f32 v[32:33], v[32:33], v[118:119]
	v_sub_f32_e32 v94, v94, v95
	v_add_f32_e32 v32, v32, v33
	v_mul_f32_e32 v95, 0x3e0293ee, v32
	v_mul_f32_e32 v94, 0x3e0293ee, v94
	v_cvt_pk_bf16_f32 v172, v109, v121
	s_waitcnt vmcnt(6)
	v_pk_mul_f32 v[32:33], v[76:77], v[78:79] op_sel:[1,0] op_sel_hi:[0,1]
	v_sub_f32_e32 v32, v32, v33
	v_mul_f32_e32 v116, 0x3e0293ee, v32
	v_pk_mul_f32 v[32:33], v[76:77], v[78:79]
	v_cvt_pk_bf16_f32 v173, v127, v125
	v_cvt_pk_bf16_f32 v174, v123, v111
	v_cvt_pk_bf16_f32 v175, v107, v129
	v_cvt_pk_bf16_f32 v168, v101, v99
	v_cvt_pk_bf16_f32 v169, v97, v113
	s_nop 0
	v_add_f32_e32 v32, v32, v33
	v_mul_f32_e32 v76, 0x3e0293ee, v32
	v_pk_mul_f32 v[32:33], v[74:75], v[80:81] op_sel:[1,0] op_sel_hi:[0,1]
	v_sub_f32_e32 v32, v32, v33
	v_mul_f32_e32 v77, 0x3e0293ee, v32
	v_pk_mul_f32 v[32:33], v[74:75], v[80:81]
	v_cvt_pk_bf16_f32 v170, v115, v131
	v_cvt_pk_bf16_f32 v171, v133, v94
	v_cvt_pk_bf16_f32 v164, v120, v126
	v_cvt_pk_bf16_f32 v165, v124, v122
	v_cvt_pk_bf16_f32 v166, v110, v106
	s_nop 0
	v_add_f32_e32 v32, v32, v33
	v_mul_f32_e32 v74, 0x3e0293ee, v32
	v_pk_mul_f32 v[32:33], v[72:73], v[64:65] op_sel:[1,0] op_sel_hi:[0,1]
	v_sub_f32_e32 v32, v32, v33
	v_mul_f32_e32 v75, 0x3e0293ee, v32
	v_pk_mul_f32 v[32:33], v[72:73], v[64:65]
	v_cvt_pk_bf16_f32 v167, v128, v100
	v_cvt_pk_bf16_f32 v160, v98, v96
	v_cvt_pk_bf16_f32 v161, v112, v114
	v_cvt_pk_bf16_f32 v162, v130, v132
	v_cvt_pk_bf16_f32 v163, v108, v95
	s_nop 0
	v_add_f32_e32 v32, v32, v33
	v_mul_f32_e32 v64, 0x3e0293ee, v32
	v_pk_mul_f32 v[32:33], v[70:71], v[66:67] op_sel:[1,0] op_sel_hi:[0,1]
	v_sub_f32_e32 v32, v32, v33
	v_mul_f32_e32 v65, 0x3e0293ee, v32
	v_pk_mul_f32 v[32:33], v[70:71], v[66:67]
	v_cvt_pk_bf16_f32 v156, v116, v77
	v_cvt_pk_bf16_f32 v157, v75, v65
	v_mov_b32_e32 v65, v181
	v_add_f32_e32 v32, v32, v33
	v_mul_f32_e32 v66, 0x3e0293ee, v32
	s_waitcnt vmcnt(4)
	v_pk_mul_f32 v[32:33], v[68:69], v[102:103] op_sel:[1,0] op_sel_hi:[0,1]
	v_sub_f32_e32 v32, v32, v33
	v_mul_f32_e32 v67, 0x3e0293ee, v32
	v_pk_mul_f32 v[32:33], v[68:69], v[102:103]
	v_mov_b32_e32 v70, v181
	v_add_f32_e32 v32, v32, v33
	v_mul_f32_e32 v68, 0x3e0293ee, v32
	v_pk_mul_f32 v[32:33], v[62:63], v[104:105] op_sel:[1,0] op_sel_hi:[0,1]
	v_sub_f32_e32 v32, v32, v33
	v_mul_f32_e32 v69, 0x3e0293ee, v32
	v_pk_mul_f32 v[32:33], v[62:63], v[104:105]
	v_cvt_pk_bf16_f32 v158, v67, v69
	v_mov_b32_e32 v67, v181
	v_add_f32_e32 v32, v32, v33
	v_mul_f32_e32 v62, 0x3e0293ee, v32
	v_pk_mul_f32 v[32:33], v[60:61], v[82:83] op_sel:[1,0] op_sel_hi:[0,1]
	v_sub_f32_e32 v32, v32, v33
	v_mul_f32_e32 v63, 0x3e0293ee, v32
	v_pk_mul_f32 v[32:33], v[60:61], v[82:83]
	v_mov_b32_e32 v69, v181
	v_add_f32_e32 v32, v32, v33
	v_mul_f32_e32 v60, 0x3e0293ee, v32
	v_pk_mul_f32 v[32:33], v[58:59], v[84:85] op_sel:[1,0] op_sel_hi:[0,1]
	v_sub_f32_e32 v32, v32, v33
	v_mul_f32_e32 v61, 0x3e0293ee, v32
	v_pk_mul_f32 v[32:33], v[58:59], v[84:85]
	v_cvt_pk_bf16_f32 v159, v63, v61
	v_mov_b32_e32 v61, v181
	v_add_f32_e32 v32, v32, v33
	v_mul_f32_e32 v58, 0x3e0293ee, v32
	s_waitcnt vmcnt(2)
	v_pk_mul_f32 v[32:33], v[56:57], v[90:91] op_sel:[1,0] op_sel_hi:[0,1]
	v_sub_f32_e32 v32, v32, v33
	v_mul_f32_e32 v59, 0x3e0293ee, v32
	v_pk_mul_f32 v[32:33], v[56:57], v[90:91]
	v_mov_b32_e32 v63, v181
	v_add_f32_e32 v32, v32, v33
	v_mul_f32_e32 v56, 0x3e0293ee, v32
	v_pk_mul_f32 v[32:33], v[54:55], v[92:93] op_sel:[1,0] op_sel_hi:[0,1]
	v_sub_f32_e32 v32, v32, v33
	v_mul_f32_e32 v57, 0x3e0293ee, v32
	v_pk_mul_f32 v[32:33], v[54:55], v[92:93]
	v_cvt_pk_bf16_f32 v152, v59, v57
	v_mov_b32_e32 v57, v181
	v_add_f32_e32 v32, v32, v33
	v_mul_f32_e32 v54, 0x3e0293ee, v32
	v_pk_mul_f32 v[32:33], v[52:53], v[86:87] op_sel:[1,0] op_sel_hi:[0,1]
	v_sub_f32_e32 v32, v32, v33
	v_mul_f32_e32 v55, 0x3e0293ee, v32
	v_pk_mul_f32 v[32:33], v[52:53], v[86:87]
	v_mov_b32_e32 v59, v181
	v_add_f32_e32 v32, v32, v33
	v_mul_f32_e32 v52, 0x3e0293ee, v32
	v_pk_mul_f32 v[32:33], v[50:51], v[88:89] op_sel:[1,0] op_sel_hi:[0,1]
	v_sub_f32_e32 v32, v32, v33
	v_mul_f32_e32 v53, 0x3e0293ee, v32
	v_pk_mul_f32 v[32:33], v[50:51], v[88:89]
	v_cvt_pk_bf16_f32 v153, v55, v53
	v_mov_b32_e32 v71, v181
	v_add_f32_e32 v32, v32, v33
	v_mul_f32_e32 v50, 0x3e0293ee, v32
	s_waitcnt vmcnt(0)
	v_pk_mul_f32 v[32:33], v[48:49], v[40:41] op_sel:[1,0] op_sel_hi:[0,1]
	v_sub_f32_e32 v32, v32, v33
	v_mul_f32_e32 v51, 0x3e0293ee, v32
	v_pk_mul_f32 v[32:33], v[48:49], v[40:41]
	v_mov_b32_e32 v72, v181
	v_add_f32_e32 v32, v32, v33
	v_mul_f32_e32 v40, 0x3e0293ee, v32
	v_pk_mul_f32 v[32:33], v[46:47], v[42:43] op_sel:[1,0] op_sel_hi:[0,1]
	v_sub_f32_e32 v32, v32, v33
	v_mul_f32_e32 v41, 0x3e0293ee, v32
	v_pk_mul_f32 v[32:33], v[46:47], v[42:43]
	v_cvt_pk_bf16_f32 v154, v51, v41
	v_mov_b32_e32 v73, v181
	v_add_f32_e32 v32, v32, v33
	v_mul_f32_e32 v42, 0x3e0293ee, v32
	v_pk_mul_f32 v[32:33], v[44:45], v[36:37] op_sel:[1,0] op_sel_hi:[0,1]
	v_sub_f32_e32 v32, v32, v33
	v_mul_f32_e32 v43, 0x3e0293ee, v32
	v_pk_mul_f32 v[32:33], v[44:45], v[36:37]
	v_mov_b32_e32 v75, v181
	v_add_f32_e32 v32, v32, v33
	v_mul_f32_e32 v36, 0x3e0293ee, v32
	v_pk_mul_f32 v[32:33], v[34:35], v[38:39] op_sel:[1,0] op_sel_hi:[0,1]
	v_sub_f32_e32 v32, v32, v33
	v_mul_f32_e32 v37, 0x3e0293ee, v32
	v_pk_mul_f32 v[32:33], v[34:35], v[38:39]
	v_cvt_pk_bf16_f32 v155, v43, v37
	v_cvt_pk_bf16_f32 v148, v76, v74
	v_cvt_pk_bf16_f32 v149, v64, v66
	v_cvt_pk_bf16_f32 v150, v68, v62
	v_cvt_pk_bf16_f32 v151, v60, v58
	s_nop 0
	v_add_f32_e32 v32, v32, v33
	v_mul_f32_e32 v32, 0x3e0293ee, v32
	v_cvt_pk_bf16_f32 v144, v56, v54
	v_cvt_pk_bf16_f32 v145, v52, v50
	v_cvt_pk_bf16_f32 v146, v40, v42
	v_cvt_pk_bf16_f32 v147, v36, v32
	v_and_or_b32 v32, s8, 32, v178
	v_lshl_add_u32 v206, v176, 4, 16
	s_lshr_b32 s0, s97, 3
	s_and_b32 s0, s0, 0x1ffffff0
	v_mov_b32_e32 v33, s0
	v_mad_u32_u24 v32, v32, s82, v33
	v_lshl_or_b32 v32, v179, 3, v32
	v_lshlrev_b32_e32 v180, 1, v32
	s_lshr_b32 s0, s97, 4
	s_and_b32 s5, s0, 0xffffff0
	s_lshr_b32 s0, s97, 5
	v_and_or_b32 v32, s0, 2, v179
	s_lshr_b32 s18, s97, 4
	s_and_b32 s18, s18, 8
	v_bfe_u32 v33, v177, 2, 3
	v_or_b32_e32 v33, s5, v33
	v_or_b32_e32 v33, s18, v33
	v_lshlrev_b32_e32 v32, 5, v32
	v_mul_lo_u32 v33, v33, s82
	v_or3_b32 v32, v32, v204, v33
	v_lshlrev_b32_e32 v199, 1, v32
	v_add_u32_e32 v198, 0x80, v180
	v_add_u32_e32 v219, 0x48000, v199
	s_lshl_b32 s0, s33, 10
	s_add_i32 s74, s0, 16
	s_add_i32 s68, s0, 0x10010
	s_add_i32 m0, s74, 0
	s_nop 0
	global_load_lds_dwordx4 v180, s[72:73]
	s_add_i32 m0, s74, 8192
	s_nop 0
	global_load_lds_dwordx4 v198, s[72:73]
	s_add_u32 s72, s72, 0x90000
	s_addc_u32 s73, s73, 0
	s_add_i32 m0, s74, 16384
	s_nop 0
	global_load_lds_dwordx4 v180, s[72:73]
	s_add_i32 m0, s74, 24576
	s_nop 0
	global_load_lds_dwordx4 v198, s[72:73]
	s_add_u32 s72, s72, 0x90000
	s_addc_u32 s73, s73, 0
	s_add_i32 m0, s68, 0
	s_nop 0
	global_load_lds_dwordx4 v199, s[70:71]
	s_add_i32 m0, s68, 8192
	s_nop 0
	global_load_lds_dwordx4 v219, s[70:71]
	s_add_u32 s70, s70, 0x90000
	s_addc_u32 s71, s71, 0
	s_add_i32 m0, s74, 32768
	s_nop 0
	global_load_lds_dwordx4 v180, s[72:73]
	s_add_i32 m0, s74, 40960
	s_nop 0
	global_load_lds_dwordx4 v198, s[72:73]
	s_add_u32 s72, s72, 0x90000
	s_addc_u32 s73, s73, 0
	s_add_i32 m0, s68, 16384
	s_nop 0
	global_load_lds_dwordx4 v199, s[70:71]
	s_add_i32 m0, s68, 24576
	s_nop 0
	global_load_lds_dwordx4 v219, s[70:71]
	s_add_u32 s70, s70, 0x90000
	s_addc_u32 s71, s71, 0
	s_add_i32 m0, s74, 49152
	s_nop 0
	global_load_lds_dwordx4 v180, s[72:73]
	s_add_i32 m0, s74, 57344
	s_nop 0
	global_load_lds_dwordx4 v198, s[72:73]
	s_add_u32 s72, s72, 0x90000
	s_addc_u32 s73, s73, 0
	s_add_i32 m0, s68, 32768
	s_nop 0
	global_load_lds_dwordx4 v199, s[70:71]
	s_add_i32 m0, s68, 40960
	s_nop 0
	global_load_lds_dwordx4 v219, s[70:71]
	s_add_u32 s70, s70, 0x90000
	s_addc_u32 s71, s71, 0
	v_mov_b32_e32 v80, 0
	v_mov_b32_e32 v81, 0
	v_mov_b32_e32 v82, 0
	v_mov_b32_e32 v83, 0
	v_mov_b32_e32 v84, 0
	v_mov_b32_e32 v85, 0
	v_mov_b32_e32 v86, 0
	v_mov_b32_e32 v87, 0
	v_mov_b32_e32 v88, 0
	v_mov_b32_e32 v89, 0
	v_mov_b32_e32 v90, 0
	v_mov_b32_e32 v91, 0
	v_mov_b32_e32 v92, 0
	v_mov_b32_e32 v93, 0
	v_mov_b32_e32 v94, 0
	v_mov_b32_e32 v95, 0
	v_mov_b32_e32 v64, 0
	v_mov_b32_e32 v65, 0
	v_mov_b32_e32 v66, 0
	v_mov_b32_e32 v67, 0
	v_mov_b32_e32 v68, 0
	v_mov_b32_e32 v69, 0
	v_mov_b32_e32 v70, 0
	v_mov_b32_e32 v71, 0
	v_mov_b32_e32 v72, 0
	v_mov_b32_e32 v73, 0
	v_mov_b32_e32 v74, 0
	v_mov_b32_e32 v75, 0
	v_mov_b32_e32 v76, 0
	v_mov_b32_e32 v77, 0
	v_mov_b32_e32 v78, 0
	v_mov_b32_e32 v79, 0
	v_mov_b32_e32 v48, 0
	v_mov_b32_e32 v49, 0
	v_mov_b32_e32 v50, 0
	v_mov_b32_e32 v51, 0
	v_mov_b32_e32 v52, 0
	v_mov_b32_e32 v53, 0
	v_mov_b32_e32 v54, 0
	v_mov_b32_e32 v55, 0
	v_mov_b32_e32 v56, 0
	v_mov_b32_e32 v57, 0
	v_mov_b32_e32 v58, 0
	v_mov_b32_e32 v59, 0
	v_mov_b32_e32 v60, 0
	v_mov_b32_e32 v61, 0
	v_mov_b32_e32 v62, 0
	v_mov_b32_e32 v63, 0
	v_mov_b32_e32 v32, 0
	v_mov_b32_e32 v33, 0
	v_mov_b32_e32 v34, 0
	v_mov_b32_e32 v35, 0
	v_mov_b32_e32 v36, 0
	v_mov_b32_e32 v37, 0
	v_mov_b32_e32 v38, 0
	v_mov_b32_e32 v39, 0
	v_mov_b32_e32 v40, 0
	v_mov_b32_e32 v41, 0
	v_mov_b32_e32 v42, 0
	v_mov_b32_e32 v43, 0
	v_mov_b32_e32 v44, 0
	v_mov_b32_e32 v45, 0
	v_mov_b32_e32 v46, 0
	v_mov_b32_e32 v47, 0
	v_mov_b32_e32 v218, 0
	v_mov_b32_e32 v248, 0
	v_mov_b32_e32 v249, 0
	v_mov_b32_e32 v251, 0
	s_waitcnt vmcnt(4)
	s_barrier
	s_cmp_lt_u32 s33, 4
	s_cbranch_scc1 .Lattn_lead_in
	s_barrier
.Lattn_lead_in:
	ds_read_b128 v[236:239], v206 offset:0
	ds_read_b128 v[240:243], v206 offset:2048
	ds_read_b128 v[244:247], v206 offset:4096
	ds_read_b128 v[190:193], v206 offset:6144
	ds_read_b128 v[194:197], v206 offset:8192
	s_setprio 1
	s_waitcnt lgkmcnt(4)
	v_mfma_f32_32x32x16_bf16 v[96:111], v[236:239], v[172:175], v[16:31]
	ds_read_b128 v[252:255], v206 offset:10240
	s_waitcnt lgkmcnt(4)
	v_mfma_f32_32x32x16_bf16 v[96:111], v[240:243], v[168:171], v[96:111]
	ds_read_b128 v[236:239], v206 offset:12288
	s_waitcnt lgkmcnt(4)
	v_mfma_f32_32x32x16_bf16 v[96:111], v[244:247], v[164:167], v[96:111]
	ds_read_b128 v[240:243], v206 offset:14336
	s_waitcnt lgkmcnt(4)
	v_mfma_f32_32x32x16_bf16 v[96:111], v[190:193], v[160:163], v[96:111]
	ds_read_b128 v[244:247], v206 offset:1024
	s_waitcnt lgkmcnt(4)
	v_mfma_f32_32x32x16_bf16 v[96:111], v[194:197], v[156:159], v[96:111]
	ds_read_b128 v[190:193], v206 offset:3072
	s_waitcnt lgkmcnt(4)
	v_mfma_f32_32x32x16_bf16 v[96:111], v[252:255], v[152:155], v[96:111]
	ds_read_b128 v[194:197], v206 offset:5120
	s_waitcnt lgkmcnt(4)
	v_mfma_f32_32x32x16_bf16 v[96:111], v[236:239], v[148:151], v[96:111]
	ds_read_b128 v[252:255], v206 offset:7168
	s_waitcnt lgkmcnt(4)
	v_mfma_f32_32x32x16_bf16 v[96:111], v[240:243], v[144:147], v[96:111]
	ds_read_b128 v[236:239], v206 offset:9216
	s_waitcnt lgkmcnt(4)
	v_mfma_f32_32x32x16_bf16 v[112:127], v[244:247], v[172:175], v[16:31]
	ds_read_b128 v[240:243], v206 offset:11264
	s_waitcnt lgkmcnt(4)
	v_mfma_f32_32x32x16_bf16 v[112:127], v[190:193], v[168:171], v[112:127]
	ds_read_b128 v[244:247], v206 offset:13312
	s_waitcnt lgkmcnt(4)
	v_mfma_f32_32x32x16_bf16 v[112:127], v[194:197], v[164:167], v[112:127]
	ds_read_b128 v[190:193], v206 offset:15360
	s_waitcnt lgkmcnt(4)
	v_mfma_f32_32x32x16_bf16 v[112:127], v[252:255], v[160:163], v[112:127]
	s_waitcnt lgkmcnt(3)
	v_mfma_f32_32x32x16_bf16 v[112:127], v[236:239], v[156:159], v[112:127]
	s_waitcnt lgkmcnt(2)
	v_mfma_f32_32x32x16_bf16 v[112:127], v[240:243], v[152:155], v[112:127]
	s_waitcnt lgkmcnt(1)
	v_mfma_f32_32x32x16_bf16 v[112:127], v[244:247], v[148:151], v[112:127]
	s_waitcnt lgkmcnt(0)
	v_mfma_f32_32x32x16_bf16 v[112:127], v[190:193], v[144:147], v[112:127]
	s_setprio 0
	s_waitcnt vmcnt(4) lgkmcnt(0)
	s_barrier
	ds_read_b128 v[236:239], v206 offset:16384
	ds_read_b128 v[240:243], v206 offset:18432
	ds_read_b128 v[244:247], v206 offset:20480
	ds_read_b128 v[190:193], v206 offset:22528
	ds_read_b128 v[194:197], v206 offset:24576
	v_exp_f32_e32 v96, v96
	v_exp_f32_e32 v97, v97
	v_exp_f32_e32 v98, v98
	v_exp_f32_e32 v99, v99
	v_exp_f32_e32 v100, v100
	v_exp_f32_e32 v101, v101
	v_exp_f32_e32 v102, v102
	v_exp_f32_e32 v103, v103
	v_exp_f32_e32 v104, v104
	v_exp_f32_e32 v105, v105
	v_exp_f32_e32 v106, v106
	v_exp_f32_e32 v107, v107
	v_exp_f32_e32 v108, v108
	v_exp_f32_e32 v109, v109
	v_exp_f32_e32 v110, v110
	v_exp_f32_e32 v111, v111
	v_exp_f32_e32 v112, v112
	v_exp_f32_e32 v113, v113
	v_exp_f32_e32 v114, v114
	v_exp_f32_e32 v115, v115
	v_exp_f32_e32 v116, v116
	v_exp_f32_e32 v117, v117
	v_exp_f32_e32 v118, v118
	v_exp_f32_e32 v119, v119
	v_exp_f32_e32 v120, v120
	v_exp_f32_e32 v121, v121
	v_exp_f32_e32 v122, v122
	v_exp_f32_e32 v123, v123
	v_exp_f32_e32 v124, v124
	v_exp_f32_e32 v125, v125
	v_exp_f32_e32 v126, v126
	v_exp_f32_e32 v127, v127
	v_cvt_pk_bf16_f32 v220, v96, v97
	v_cvt_pk_bf16_f32 v221, v98, v99
	v_cvt_pk_bf16_f32 v222, v100, v101
	v_cvt_pk_bf16_f32 v223, v102, v103
	v_add_f32_e32 v218, v96, v218
	v_add_f32_e32 v248, v97, v248
	v_add_f32_e32 v218, v98, v218
	v_add_f32_e32 v248, v99, v248
	v_add_f32_e32 v218, v100, v218
	v_add_f32_e32 v248, v101, v248
	v_add_f32_e32 v218, v102, v218
	v_add_f32_e32 v248, v103, v248
	v_cvt_pk_bf16_f32 v224, v104, v105
	v_cvt_pk_bf16_f32 v225, v106, v107
	v_cvt_pk_bf16_f32 v226, v108, v109
	v_cvt_pk_bf16_f32 v227, v110, v111
	v_add_f32_e32 v218, v104, v218
	v_add_f32_e32 v248, v105, v248
	v_add_f32_e32 v218, v106, v218
	v_add_f32_e32 v248, v107, v248
	v_add_f32_e32 v218, v108, v218
	v_add_f32_e32 v248, v109, v248
	v_add_f32_e32 v218, v110, v218
	v_add_f32_e32 v248, v111, v248
	v_cvt_pk_bf16_f32 v228, v112, v113
	v_cvt_pk_bf16_f32 v229, v114, v115
	v_cvt_pk_bf16_f32 v230, v116, v117
	v_cvt_pk_bf16_f32 v231, v118, v119
	v_add_f32_e32 v249, v112, v249
	v_add_f32_e32 v251, v113, v251
	v_add_f32_e32 v249, v114, v249
	v_add_f32_e32 v251, v115, v251
	v_add_f32_e32 v249, v116, v249
	v_add_f32_e32 v251, v117, v251
	v_add_f32_e32 v249, v118, v249
	v_add_f32_e32 v251, v119, v251
	v_cvt_pk_bf16_f32 v232, v120, v121
	v_cvt_pk_bf16_f32 v233, v122, v123
	v_cvt_pk_bf16_f32 v234, v124, v125
	v_cvt_pk_bf16_f32 v235, v126, v127
	v_add_f32_e32 v249, v120, v249
	v_add_f32_e32 v251, v121, v251
	v_add_f32_e32 v249, v122, v249
	v_add_f32_e32 v251, v123, v251
	v_add_f32_e32 v249, v124, v249
	v_add_f32_e32 v251, v125, v251
	v_add_f32_e32 v249, v126, v249
	v_add_f32_e32 v251, v127, v251
	s_waitcnt vmcnt(0)
	s_barrier
	s_movk_i32 s98, 63
.Lattn_loop:
	s_setprio 1
	s_waitcnt lgkmcnt(4)
	v_mfma_f32_32x32x16_bf16 v[96:111], v[236:239], v[172:175], v[16:31]
	ds_read_b128 v[252:255], v206 offset:26624
	s_waitcnt lgkmcnt(4)
	v_mfma_f32_32x32x16_bf16 v[96:111], v[240:243], v[168:171], v[96:111]
	ds_read_b128 v[236:239], v206 offset:28672
	s_waitcnt lgkmcnt(4)
	v_mfma_f32_32x32x16_bf16 v[96:111], v[244:247], v[164:167], v[96:111]
	ds_read_b128 v[240:243], v206 offset:30720
	s_waitcnt lgkmcnt(4)
	v_mfma_f32_32x32x16_bf16 v[96:111], v[190:193], v[160:163], v[96:111]
	ds_read_b128 v[244:247], v206 offset:17408
	s_waitcnt lgkmcnt(4)
	v_mfma_f32_32x32x16_bf16 v[96:111], v[194:197], v[156:159], v[96:111]
	ds_read_b128 v[190:193], v206 offset:19456
	s_waitcnt lgkmcnt(4)
	v_mfma_f32_32x32x16_bf16 v[96:111], v[252:255], v[152:155], v[96:111]
	ds_read_b128 v[194:197], v206 offset:21504
	s_waitcnt lgkmcnt(4)
	v_mfma_f32_32x32x16_bf16 v[96:111], v[236:239], v[148:151], v[96:111]
	ds_read_b128 v[252:255], v206 offset:23552
	s_waitcnt lgkmcnt(4)
	v_mfma_f32_32x32x16_bf16 v[96:111], v[240:243], v[144:147], v[96:111]
	ds_read_b128 v[236:239], v206 offset:25600
	s_waitcnt lgkmcnt(4)
	v_mfma_f32_32x32x16_bf16 v[112:127], v[244:247], v[172:175], v[16:31]
	ds_read_b128 v[240:243], v206 offset:27648
	s_waitcnt lgkmcnt(4)
	v_mfma_f32_32x32x16_bf16 v[112:127], v[190:193], v[168:171], v[112:127]
	ds_read_b128 v[244:247], v206 offset:29696
	s_waitcnt lgkmcnt(4)
	v_mfma_f32_32x32x16_bf16 v[112:127], v[194:197], v[164:167], v[112:127]
	ds_read_b128 v[190:193], v206 offset:31744
	s_waitcnt lgkmcnt(4)
	v_mfma_f32_32x32x16_bf16 v[112:127], v[252:255], v[160:163], v[112:127]
	ds_read_b64_tr_b16 v[194:195], v201 offset:0
	ds_read_b64_tr_b16 v[196:197], v201 offset:2048
	s_waitcnt lgkmcnt(5)
	v_mfma_f32_32x32x16_bf16 v[112:127], v[236:239], v[156:159], v[112:127]
	ds_read_b64_tr_b16 v[252:253], v201 offset:4096
	ds_read_b64_tr_b16 v[254:255], v201 offset:6144
	s_waitcnt lgkmcnt(6)
	v_mfma_f32_32x32x16_bf16 v[112:127], v[240:243], v[152:155], v[112:127]
	ds_read_b64_tr_b16 v[236:237], v201 offset:8192
	ds_read_b64_tr_b16 v[238:239], v201 offset:10240
	s_waitcnt lgkmcnt(7)
	v_mfma_f32_32x32x16_bf16 v[112:127], v[244:247], v[148:151], v[112:127]
	ds_read_b64_tr_b16 v[240:241], v201 offset:12288
	ds_read_b64_tr_b16 v[242:243], v201 offset:14336
	s_waitcnt lgkmcnt(8)
	v_mfma_f32_32x32x16_bf16 v[112:127], v[190:193], v[144:147], v[112:127]
	ds_read_b64_tr_b16 v[244:245], v201 offset:512
	ds_read_b64_tr_b16 v[246:247], v201 offset:2560
	s_waitcnt lgkmcnt(8)
	v_mfma_f32_32x32x16_bf16 v[80:95], v[220:223], v[194:197], v[80:95]
	ds_read_b64_tr_b16 v[190:191], v201 offset:4608
	ds_read_b64_tr_b16 v[192:193], v201 offset:6656
	s_waitcnt lgkmcnt(8)
	v_mfma_f32_32x32x16_bf16 v[80:95], v[224:227], v[252:255], v[80:95]
	ds_read_b64_tr_b16 v[194:195], v201 offset:8704
	ds_read_b64_tr_b16 v[196:197], v201 offset:10752
	s_waitcnt lgkmcnt(8)
	v_mfma_f32_32x32x16_bf16 v[80:95], v[228:231], v[236:239], v[80:95]
	ds_read_b64_tr_b16 v[252:253], v201 offset:12800
	ds_read_b64_tr_b16 v[254:255], v201 offset:14848
	s_waitcnt lgkmcnt(8)
	v_mfma_f32_32x32x16_bf16 v[80:95], v[232:235], v[240:243], v[80:95]
	ds_read_b64_tr_b16 v[236:237], v201 offset:1024
	ds_read_b64_tr_b16 v[238:239], v201 offset:3072
	s_waitcnt lgkmcnt(8)
	v_mfma_f32_32x32x16_bf16 v[64:79], v[220:223], v[244:247], v[64:79]
	ds_read_b64_tr_b16 v[240:241], v201 offset:5120
	ds_read_b64_tr_b16 v[242:243], v201 offset:7168
	s_waitcnt lgkmcnt(8)
	v_mfma_f32_32x32x16_bf16 v[64:79], v[224:227], v[190:193], v[64:79]
	ds_read_b64_tr_b16 v[244:245], v201 offset:9216
	ds_read_b64_tr_b16 v[246:247], v201 offset:11264
	s_waitcnt lgkmcnt(8)
	v_mfma_f32_32x32x16_bf16 v[64:79], v[228:231], v[194:197], v[64:79]
	ds_read_b64_tr_b16 v[190:191], v201 offset:13312
	ds_read_b64_tr_b16 v[192:193], v201 offset:15360
	s_waitcnt lgkmcnt(8)
	v_mfma_f32_32x32x16_bf16 v[64:79], v[232:235], v[252:255], v[64:79]
	ds_read_b64_tr_b16 v[194:195], v201 offset:1536
	ds_read_b64_tr_b16 v[196:197], v201 offset:3584
	s_waitcnt lgkmcnt(8)
	v_mfma_f32_32x32x16_bf16 v[48:63], v[220:223], v[236:239], v[48:63]
	ds_read_b64_tr_b16 v[252:253], v201 offset:5632
	ds_read_b64_tr_b16 v[254:255], v201 offset:7680
	s_waitcnt lgkmcnt(8)
	v_mfma_f32_32x32x16_bf16 v[48:63], v[224:227], v[240:243], v[48:63]
	ds_read_b64_tr_b16 v[236:237], v201 offset:9728
	ds_read_b64_tr_b16 v[238:239], v201 offset:11776
	s_waitcnt lgkmcnt(8)
	v_mfma_f32_32x32x16_bf16 v[48:63], v[228:231], v[244:247], v[48:63]
	ds_read_b64_tr_b16 v[240:241], v201 offset:13824
	ds_read_b64_tr_b16 v[242:243], v201 offset:15872
	s_waitcnt lgkmcnt(8)
	v_mfma_f32_32x32x16_bf16 v[48:63], v[232:235], v[190:193], v[48:63]
	s_waitcnt lgkmcnt(6)
	v_mfma_f32_32x32x16_bf16 v[32:47], v[220:223], v[194:197], v[32:47]
	s_waitcnt lgkmcnt(4)
	v_mfma_f32_32x32x16_bf16 v[32:47], v[224:227], v[252:255], v[32:47]
	s_waitcnt lgkmcnt(2)
	v_mfma_f32_32x32x16_bf16 v[32:47], v[228:231], v[236:239], v[32:47]
	s_waitcnt lgkmcnt(0)
	v_mfma_f32_32x32x16_bf16 v[32:47], v[232:235], v[240:243], v[32:47]
	s_setprio 0
	s_waitcnt vmcnt(0) lgkmcnt(0)
	s_barrier
	s_add_i32 m0, s74, 0
	v_exp_f32_e32 v96, v96
	v_exp_f32_e32 v97, v97
	v_exp_f32_e32 v98, v98
	global_load_lds_dwordx4 v180, s[72:73]
	s_add_i32 m0, s74, 8192
	v_exp_f32_e32 v99, v99
	v_exp_f32_e32 v100, v100
	v_exp_f32_e32 v101, v101
	global_load_lds_dwordx4 v198, s[72:73]
	s_add_u32 s72, s72, 0x90000
	s_addc_u32 s73, s73, 0
	s_add_i32 m0, s68, 49152
	v_exp_f32_e32 v102, v102
	v_exp_f32_e32 v103, v103
	v_exp_f32_e32 v104, v104
	global_load_lds_dwordx4 v199, s[70:71]
	s_add_i32 m0, s68, 57344
	v_exp_f32_e32 v105, v105
	v_exp_f32_e32 v106, v106
	v_exp_f32_e32 v107, v107
	global_load_lds_dwordx4 v219, s[70:71]
	s_add_u32 s70, s70, 0x90000
	s_addc_u32 s71, s71, 0
	ds_read_b128 v[236:239], v206 offset:32768
	ds_read_b128 v[240:243], v206 offset:34816
	ds_read_b128 v[244:247], v206 offset:36864
	ds_read_b128 v[190:193], v206 offset:38912
	ds_read_b128 v[194:197], v206 offset:40960
	v_exp_f32_e32 v108, v108
	v_exp_f32_e32 v109, v109
	v_exp_f32_e32 v110, v110
	v_exp_f32_e32 v111, v111
	v_exp_f32_e32 v112, v112
	v_exp_f32_e32 v113, v113
	v_exp_f32_e32 v114, v114
	v_exp_f32_e32 v115, v115
	v_exp_f32_e32 v116, v116
	v_exp_f32_e32 v117, v117
	v_exp_f32_e32 v118, v118
	v_exp_f32_e32 v119, v119
	v_exp_f32_e32 v120, v120
	v_exp_f32_e32 v121, v121
	v_exp_f32_e32 v122, v122
	v_exp_f32_e32 v123, v123
	v_exp_f32_e32 v124, v124
	v_exp_f32_e32 v125, v125
	v_exp_f32_e32 v126, v126
	v_exp_f32_e32 v127, v127
	v_cvt_pk_bf16_f32 v220, v96, v97
	v_cvt_pk_bf16_f32 v221, v98, v99
	v_cvt_pk_bf16_f32 v222, v100, v101
	v_cvt_pk_bf16_f32 v223, v102, v103
	v_add_f32_e32 v218, v96, v218
	v_add_f32_e32 v248, v97, v248
	v_add_f32_e32 v218, v98, v218
	v_add_f32_e32 v248, v99, v248
	v_add_f32_e32 v218, v100, v218
	v_add_f32_e32 v248, v101, v248
	v_add_f32_e32 v218, v102, v218
	v_add_f32_e32 v248, v103, v248
	v_cvt_pk_bf16_f32 v224, v104, v105
	v_cvt_pk_bf16_f32 v225, v106, v107
	v_cvt_pk_bf16_f32 v226, v108, v109
	v_cvt_pk_bf16_f32 v227, v110, v111
	v_add_f32_e32 v218, v104, v218
	v_add_f32_e32 v248, v105, v248
	v_add_f32_e32 v218, v106, v218
	v_add_f32_e32 v248, v107, v248
	v_add_f32_e32 v218, v108, v218
	v_add_f32_e32 v248, v109, v248
	v_add_f32_e32 v218, v110, v218
	v_add_f32_e32 v248, v111, v248
	v_cvt_pk_bf16_f32 v228, v112, v113
	v_cvt_pk_bf16_f32 v229, v114, v115
	v_cvt_pk_bf16_f32 v230, v116, v117
	v_cvt_pk_bf16_f32 v231, v118, v119
	v_add_f32_e32 v249, v112, v249
	v_add_f32_e32 v251, v113, v251
	v_add_f32_e32 v249, v114, v249
	v_add_f32_e32 v251, v115, v251
	v_add_f32_e32 v249, v116, v249
	v_add_f32_e32 v251, v117, v251
	v_add_f32_e32 v249, v118, v249
	v_add_f32_e32 v251, v119, v251
	v_cvt_pk_bf16_f32 v232, v120, v121
	v_cvt_pk_bf16_f32 v233, v122, v123
	v_cvt_pk_bf16_f32 v234, v124, v125
	v_cvt_pk_bf16_f32 v235, v126, v127
	v_add_f32_e32 v249, v120, v249
	v_add_f32_e32 v251, v121, v251
	v_add_f32_e32 v249, v122, v249
	v_add_f32_e32 v251, v123, v251
	v_add_f32_e32 v249, v124, v249
	v_add_f32_e32 v251, v125, v251
	v_add_f32_e32 v249, v126, v249
	v_add_f32_e32 v251, v127, v251
	s_waitcnt vmcnt(4)
	s_barrier
	s_setprio 1
	s_waitcnt lgkmcnt(4)
	v_mfma_f32_32x32x16_bf16 v[96:111], v[236:239], v[172:175], v[16:31]
	ds_read_b128 v[252:255], v206 offset:43008
	s_waitcnt lgkmcnt(4)
	v_mfma_f32_32x32x16_bf16 v[96:111], v[240:243], v[168:171], v[96:111]
	ds_read_b128 v[236:239], v206 offset:45056
	s_waitcnt lgkmcnt(4)
	v_mfma_f32_32x32x16_bf16 v[96:111], v[244:247], v[164:167], v[96:111]
	ds_read_b128 v[240:243], v206 offset:47104
	s_waitcnt lgkmcnt(4)
	v_mfma_f32_32x32x16_bf16 v[96:111], v[190:193], v[160:163], v[96:111]
	ds_read_b128 v[244:247], v206 offset:33792
	s_waitcnt lgkmcnt(4)
	v_mfma_f32_32x32x16_bf16 v[96:111], v[194:197], v[156:159], v[96:111]
	ds_read_b128 v[190:193], v206 offset:35840
	s_waitcnt lgkmcnt(4)
	v_mfma_f32_32x32x16_bf16 v[96:111], v[252:255], v[152:155], v[96:111]
	ds_read_b128 v[194:197], v206 offset:37888
	s_waitcnt lgkmcnt(4)
	v_mfma_f32_32x32x16_bf16 v[96:111], v[236:239], v[148:151], v[96:111]
	ds_read_b128 v[252:255], v206 offset:39936
	s_waitcnt lgkmcnt(4)
	v_mfma_f32_32x32x16_bf16 v[96:111], v[240:243], v[144:147], v[96:111]
	ds_read_b128 v[236:239], v206 offset:41984
	s_waitcnt lgkmcnt(4)
	v_mfma_f32_32x32x16_bf16 v[112:127], v[244:247], v[172:175], v[16:31]
	ds_read_b128 v[240:243], v206 offset:44032
	s_waitcnt lgkmcnt(4)
	v_mfma_f32_32x32x16_bf16 v[112:127], v[190:193], v[168:171], v[112:127]
	ds_read_b128 v[244:247], v206 offset:46080
	s_waitcnt lgkmcnt(4)
	v_mfma_f32_32x32x16_bf16 v[112:127], v[194:197], v[164:167], v[112:127]
	ds_read_b128 v[190:193], v206 offset:48128
	s_waitcnt lgkmcnt(4)
	v_mfma_f32_32x32x16_bf16 v[112:127], v[252:255], v[160:163], v[112:127]
	ds_read_b64_tr_b16 v[194:195], v201 offset:16384
	ds_read_b64_tr_b16 v[196:197], v201 offset:18432
	s_waitcnt lgkmcnt(5)
	v_mfma_f32_32x32x16_bf16 v[112:127], v[236:239], v[156:159], v[112:127]
	ds_read_b64_tr_b16 v[252:253], v201 offset:20480
	ds_read_b64_tr_b16 v[254:255], v201 offset:22528
	s_waitcnt lgkmcnt(6)
	v_mfma_f32_32x32x16_bf16 v[112:127], v[240:243], v[152:155], v[112:127]
	ds_read_b64_tr_b16 v[236:237], v201 offset:24576
	ds_read_b64_tr_b16 v[238:239], v201 offset:26624
	s_waitcnt lgkmcnt(7)
	v_mfma_f32_32x32x16_bf16 v[112:127], v[244:247], v[148:151], v[112:127]
	ds_read_b64_tr_b16 v[240:241], v201 offset:28672
	ds_read_b64_tr_b16 v[242:243], v201 offset:30720
	s_waitcnt lgkmcnt(8)
	v_mfma_f32_32x32x16_bf16 v[112:127], v[190:193], v[144:147], v[112:127]
	ds_read_b64_tr_b16 v[244:245], v201 offset:16896
	ds_read_b64_tr_b16 v[246:247], v201 offset:18944
	s_waitcnt lgkmcnt(8)
	v_mfma_f32_32x32x16_bf16 v[80:95], v[220:223], v[194:197], v[80:95]
	ds_read_b64_tr_b16 v[190:191], v201 offset:20992
	ds_read_b64_tr_b16 v[192:193], v201 offset:23040
	s_waitcnt lgkmcnt(8)
	v_mfma_f32_32x32x16_bf16 v[80:95], v[224:227], v[252:255], v[80:95]
	ds_read_b64_tr_b16 v[194:195], v201 offset:25088
	ds_read_b64_tr_b16 v[196:197], v201 offset:27136
	s_waitcnt lgkmcnt(8)
	v_mfma_f32_32x32x16_bf16 v[80:95], v[228:231], v[236:239], v[80:95]
	ds_read_b64_tr_b16 v[252:253], v201 offset:29184
	ds_read_b64_tr_b16 v[254:255], v201 offset:31232
	s_waitcnt lgkmcnt(8)
	v_mfma_f32_32x32x16_bf16 v[80:95], v[232:235], v[240:243], v[80:95]
	ds_read_b64_tr_b16 v[236:237], v201 offset:17408
	ds_read_b64_tr_b16 v[238:239], v201 offset:19456
	s_waitcnt lgkmcnt(8)
	v_mfma_f32_32x32x16_bf16 v[64:79], v[220:223], v[244:247], v[64:79]
	ds_read_b64_tr_b16 v[240:241], v201 offset:21504
	ds_read_b64_tr_b16 v[242:243], v201 offset:23552
	s_waitcnt lgkmcnt(8)
	v_mfma_f32_32x32x16_bf16 v[64:79], v[224:227], v[190:193], v[64:79]
	ds_read_b64_tr_b16 v[244:245], v201 offset:25600
	ds_read_b64_tr_b16 v[246:247], v201 offset:27648
	s_waitcnt lgkmcnt(8)
	v_mfma_f32_32x32x16_bf16 v[64:79], v[228:231], v[194:197], v[64:79]
	ds_read_b64_tr_b16 v[190:191], v201 offset:29696
	ds_read_b64_tr_b16 v[192:193], v201 offset:31744
	s_waitcnt lgkmcnt(8)
	v_mfma_f32_32x32x16_bf16 v[64:79], v[232:235], v[252:255], v[64:79]
	ds_read_b64_tr_b16 v[194:195], v201 offset:17920
	ds_read_b64_tr_b16 v[196:197], v201 offset:19968
	s_waitcnt lgkmcnt(8)
	v_mfma_f32_32x32x16_bf16 v[48:63], v[220:223], v[236:239], v[48:63]
	ds_read_b64_tr_b16 v[252:253], v201 offset:22016
	ds_read_b64_tr_b16 v[254:255], v201 offset:24064
	s_waitcnt lgkmcnt(8)
	v_mfma_f32_32x32x16_bf16 v[48:63], v[224:227], v[240:243], v[48:63]
	ds_read_b64_tr_b16 v[236:237], v201 offset:26112
	ds_read_b64_tr_b16 v[238:239], v201 offset:28160
	s_waitcnt lgkmcnt(8)
	v_mfma_f32_32x32x16_bf16 v[48:63], v[228:231], v[244:247], v[48:63]
	ds_read_b64_tr_b16 v[240:241], v201 offset:30208
	ds_read_b64_tr_b16 v[242:243], v201 offset:32256
	s_waitcnt lgkmcnt(8)
	v_mfma_f32_32x32x16_bf16 v[48:63], v[232:235], v[190:193], v[48:63]
	s_waitcnt lgkmcnt(6)
	v_mfma_f32_32x32x16_bf16 v[32:47], v[220:223], v[194:197], v[32:47]
	s_waitcnt lgkmcnt(4)
	v_mfma_f32_32x32x16_bf16 v[32:47], v[224:227], v[252:255], v[32:47]
	s_waitcnt lgkmcnt(2)
	v_mfma_f32_32x32x16_bf16 v[32:47], v[228:231], v[236:239], v[32:47]
	s_waitcnt lgkmcnt(0)
	v_mfma_f32_32x32x16_bf16 v[32:47], v[232:235], v[240:243], v[32:47]
	s_setprio 0
	s_waitcnt vmcnt(4) lgkmcnt(0)
	s_barrier
	s_add_i32 m0, s74, 16384
	v_exp_f32_e32 v96, v96
	v_exp_f32_e32 v97, v97
	v_exp_f32_e32 v98, v98
	global_load_lds_dwordx4 v180, s[72:73]
	s_add_i32 m0, s74, 24576
	v_exp_f32_e32 v99, v99
	v_exp_f32_e32 v100, v100
	v_exp_f32_e32 v101, v101
	global_load_lds_dwordx4 v198, s[72:73]
	s_add_u32 s72, s72, 0x90000
	s_addc_u32 s73, s73, 0
	s_add_i32 m0, s68, 0
	v_exp_f32_e32 v102, v102
	v_exp_f32_e32 v103, v103
	v_exp_f32_e32 v104, v104
	global_load_lds_dwordx4 v199, s[70:71]
	s_add_i32 m0, s68, 8192
	v_exp_f32_e32 v105, v105
	v_exp_f32_e32 v106, v106
	v_exp_f32_e32 v107, v107
	global_load_lds_dwordx4 v219, s[70:71]
	s_add_u32 s70, s70, 0x90000
	s_addc_u32 s71, s71, 0
	ds_read_b128 v[236:239], v206 offset:49152
	ds_read_b128 v[240:243], v206 offset:51200
	ds_read_b128 v[244:247], v206 offset:53248
	ds_read_b128 v[190:193], v206 offset:55296
	ds_read_b128 v[194:197], v206 offset:57344
	v_exp_f32_e32 v108, v108
	v_exp_f32_e32 v109, v109
	v_exp_f32_e32 v110, v110
	v_exp_f32_e32 v111, v111
	v_exp_f32_e32 v112, v112
	v_exp_f32_e32 v113, v113
	v_exp_f32_e32 v114, v114
	v_exp_f32_e32 v115, v115
	v_exp_f32_e32 v116, v116
	v_exp_f32_e32 v117, v117
	v_exp_f32_e32 v118, v118
	v_exp_f32_e32 v119, v119
	v_exp_f32_e32 v120, v120
	v_exp_f32_e32 v121, v121
	v_exp_f32_e32 v122, v122
	v_exp_f32_e32 v123, v123
	v_exp_f32_e32 v124, v124
	v_exp_f32_e32 v125, v125
	v_exp_f32_e32 v126, v126
	v_exp_f32_e32 v127, v127
	v_cvt_pk_bf16_f32 v220, v96, v97
	v_cvt_pk_bf16_f32 v221, v98, v99
	v_cvt_pk_bf16_f32 v222, v100, v101
	v_cvt_pk_bf16_f32 v223, v102, v103
	v_add_f32_e32 v218, v96, v218
	v_add_f32_e32 v248, v97, v248
	v_add_f32_e32 v218, v98, v218
	v_add_f32_e32 v248, v99, v248
	v_add_f32_e32 v218, v100, v218
	v_add_f32_e32 v248, v101, v248
	v_add_f32_e32 v218, v102, v218
	v_add_f32_e32 v248, v103, v248
	v_cvt_pk_bf16_f32 v224, v104, v105
	v_cvt_pk_bf16_f32 v225, v106, v107
	v_cvt_pk_bf16_f32 v226, v108, v109
	v_cvt_pk_bf16_f32 v227, v110, v111
	v_add_f32_e32 v218, v104, v218
	v_add_f32_e32 v248, v105, v248
	v_add_f32_e32 v218, v106, v218
	v_add_f32_e32 v248, v107, v248
	v_add_f32_e32 v218, v108, v218
	v_add_f32_e32 v248, v109, v248
	v_add_f32_e32 v218, v110, v218
	v_add_f32_e32 v248, v111, v248
	v_cvt_pk_bf16_f32 v228, v112, v113
	v_cvt_pk_bf16_f32 v229, v114, v115
	v_cvt_pk_bf16_f32 v230, v116, v117
	v_cvt_pk_bf16_f32 v231, v118, v119
	v_add_f32_e32 v249, v112, v249
	v_add_f32_e32 v251, v113, v251
	v_add_f32_e32 v249, v114, v249
	v_add_f32_e32 v251, v115, v251
	v_add_f32_e32 v249, v116, v249
	v_add_f32_e32 v251, v117, v251
	v_add_f32_e32 v249, v118, v249
	v_add_f32_e32 v251, v119, v251
	v_cvt_pk_bf16_f32 v232, v120, v121
	v_cvt_pk_bf16_f32 v233, v122, v123
	v_cvt_pk_bf16_f32 v234, v124, v125
	v_cvt_pk_bf16_f32 v235, v126, v127
	v_add_f32_e32 v249, v120, v249
	v_add_f32_e32 v251, v121, v251
	v_add_f32_e32 v249, v122, v249
	v_add_f32_e32 v251, v123, v251
	v_add_f32_e32 v249, v124, v249
	v_add_f32_e32 v251, v125, v251
	v_add_f32_e32 v249, v126, v249
	v_add_f32_e32 v251, v127, v251
	s_waitcnt vmcnt(4)
	s_barrier
	s_setprio 1
	s_waitcnt lgkmcnt(4)
	v_mfma_f32_32x32x16_bf16 v[96:111], v[236:239], v[172:175], v[16:31]
	ds_read_b128 v[252:255], v206 offset:59392
	s_waitcnt lgkmcnt(4)
	v_mfma_f32_32x32x16_bf16 v[96:111], v[240:243], v[168:171], v[96:111]
	ds_read_b128 v[236:239], v206 offset:61440
	s_waitcnt lgkmcnt(4)
	v_mfma_f32_32x32x16_bf16 v[96:111], v[244:247], v[164:167], v[96:111]
	ds_read_b128 v[240:243], v206 offset:63488
	s_waitcnt lgkmcnt(4)
	v_mfma_f32_32x32x16_bf16 v[96:111], v[190:193], v[160:163], v[96:111]
	ds_read_b128 v[244:247], v206 offset:50176
	s_waitcnt lgkmcnt(4)
	v_mfma_f32_32x32x16_bf16 v[96:111], v[194:197], v[156:159], v[96:111]
	ds_read_b128 v[190:193], v206 offset:52224
	s_waitcnt lgkmcnt(4)
	v_mfma_f32_32x32x16_bf16 v[96:111], v[252:255], v[152:155], v[96:111]
	ds_read_b128 v[194:197], v206 offset:54272
	s_waitcnt lgkmcnt(4)
	v_mfma_f32_32x32x16_bf16 v[96:111], v[236:239], v[148:151], v[96:111]
	ds_read_b128 v[252:255], v206 offset:56320
	s_waitcnt lgkmcnt(4)
	v_mfma_f32_32x32x16_bf16 v[96:111], v[240:243], v[144:147], v[96:111]
	ds_read_b128 v[236:239], v206 offset:58368
	s_waitcnt lgkmcnt(4)
	v_mfma_f32_32x32x16_bf16 v[112:127], v[244:247], v[172:175], v[16:31]
	ds_read_b128 v[240:243], v206 offset:60416
	s_waitcnt lgkmcnt(4)
	v_mfma_f32_32x32x16_bf16 v[112:127], v[190:193], v[168:171], v[112:127]
	ds_read_b128 v[244:247], v206 offset:62464
	s_waitcnt lgkmcnt(4)
	v_mfma_f32_32x32x16_bf16 v[112:127], v[194:197], v[164:167], v[112:127]
	ds_read_b128 v[190:193], v206 offset:64512
	s_waitcnt lgkmcnt(4)
	v_mfma_f32_32x32x16_bf16 v[112:127], v[252:255], v[160:163], v[112:127]
	ds_read_b64_tr_b16 v[194:195], v201 offset:32768
	ds_read_b64_tr_b16 v[196:197], v201 offset:34816
	s_waitcnt lgkmcnt(5)
	v_mfma_f32_32x32x16_bf16 v[112:127], v[236:239], v[156:159], v[112:127]
	ds_read_b64_tr_b16 v[252:253], v201 offset:36864
	ds_read_b64_tr_b16 v[254:255], v201 offset:38912
	s_waitcnt lgkmcnt(6)
	v_mfma_f32_32x32x16_bf16 v[112:127], v[240:243], v[152:155], v[112:127]
	ds_read_b64_tr_b16 v[236:237], v201 offset:40960
	ds_read_b64_tr_b16 v[238:239], v201 offset:43008
	s_waitcnt lgkmcnt(7)
	v_mfma_f32_32x32x16_bf16 v[112:127], v[244:247], v[148:151], v[112:127]
	ds_read_b64_tr_b16 v[240:241], v201 offset:45056
	ds_read_b64_tr_b16 v[242:243], v201 offset:47104
	s_waitcnt lgkmcnt(8)
	v_mfma_f32_32x32x16_bf16 v[112:127], v[190:193], v[144:147], v[112:127]
	ds_read_b64_tr_b16 v[244:245], v201 offset:33280
	ds_read_b64_tr_b16 v[246:247], v201 offset:35328
	s_waitcnt lgkmcnt(8)
	v_mfma_f32_32x32x16_bf16 v[80:95], v[220:223], v[194:197], v[80:95]
	ds_read_b64_tr_b16 v[190:191], v201 offset:37376
	ds_read_b64_tr_b16 v[192:193], v201 offset:39424
	s_waitcnt lgkmcnt(8)
	v_mfma_f32_32x32x16_bf16 v[80:95], v[224:227], v[252:255], v[80:95]
	ds_read_b64_tr_b16 v[194:195], v201 offset:41472
	ds_read_b64_tr_b16 v[196:197], v201 offset:43520
	s_waitcnt lgkmcnt(8)
	v_mfma_f32_32x32x16_bf16 v[80:95], v[228:231], v[236:239], v[80:95]
	ds_read_b64_tr_b16 v[252:253], v201 offset:45568
	ds_read_b64_tr_b16 v[254:255], v201 offset:47616
	s_waitcnt lgkmcnt(8)
	v_mfma_f32_32x32x16_bf16 v[80:95], v[232:235], v[240:243], v[80:95]
	ds_read_b64_tr_b16 v[236:237], v201 offset:33792
	ds_read_b64_tr_b16 v[238:239], v201 offset:35840
	s_waitcnt lgkmcnt(8)
	v_mfma_f32_32x32x16_bf16 v[64:79], v[220:223], v[244:247], v[64:79]
	ds_read_b64_tr_b16 v[240:241], v201 offset:37888
	ds_read_b64_tr_b16 v[242:243], v201 offset:39936
	s_waitcnt lgkmcnt(8)
	v_mfma_f32_32x32x16_bf16 v[64:79], v[224:227], v[190:193], v[64:79]
	ds_read_b64_tr_b16 v[244:245], v201 offset:41984
	ds_read_b64_tr_b16 v[246:247], v201 offset:44032
	s_waitcnt lgkmcnt(8)
	v_mfma_f32_32x32x16_bf16 v[64:79], v[228:231], v[194:197], v[64:79]
	ds_read_b64_tr_b16 v[190:191], v201 offset:46080
	ds_read_b64_tr_b16 v[192:193], v201 offset:48128
	s_waitcnt lgkmcnt(8)
	v_mfma_f32_32x32x16_bf16 v[64:79], v[232:235], v[252:255], v[64:79]
	ds_read_b64_tr_b16 v[194:195], v201 offset:34304
	ds_read_b64_tr_b16 v[196:197], v201 offset:36352
	s_waitcnt lgkmcnt(8)
	v_mfma_f32_32x32x16_bf16 v[48:63], v[220:223], v[236:239], v[48:63]
	ds_read_b64_tr_b16 v[252:253], v201 offset:38400
	ds_read_b64_tr_b16 v[254:255], v201 offset:40448
	s_waitcnt lgkmcnt(8)
	v_mfma_f32_32x32x16_bf16 v[48:63], v[224:227], v[240:243], v[48:63]
	ds_read_b64_tr_b16 v[236:237], v201 offset:42496
	ds_read_b64_tr_b16 v[238:239], v201 offset:44544
	s_waitcnt lgkmcnt(8)
	v_mfma_f32_32x32x16_bf16 v[48:63], v[228:231], v[244:247], v[48:63]
	ds_read_b64_tr_b16 v[240:241], v201 offset:46592
	ds_read_b64_tr_b16 v[242:243], v201 offset:48640
	s_waitcnt lgkmcnt(8)
	v_mfma_f32_32x32x16_bf16 v[48:63], v[232:235], v[190:193], v[48:63]
	s_waitcnt lgkmcnt(6)
	v_mfma_f32_32x32x16_bf16 v[32:47], v[220:223], v[194:197], v[32:47]
	s_waitcnt lgkmcnt(4)
	v_mfma_f32_32x32x16_bf16 v[32:47], v[224:227], v[252:255], v[32:47]
	s_waitcnt lgkmcnt(2)
	v_mfma_f32_32x32x16_bf16 v[32:47], v[228:231], v[236:239], v[32:47]
	s_waitcnt lgkmcnt(0)
	v_mfma_f32_32x32x16_bf16 v[32:47], v[232:235], v[240:243], v[32:47]
	s_setprio 0
	s_waitcnt vmcnt(4) lgkmcnt(0)
	s_barrier
	s_add_i32 m0, s74, 32768
	v_exp_f32_e32 v96, v96
	v_exp_f32_e32 v97, v97
	v_exp_f32_e32 v98, v98
	global_load_lds_dwordx4 v180, s[72:73]
	s_add_i32 m0, s74, 40960
	v_exp_f32_e32 v99, v99
	v_exp_f32_e32 v100, v100
	v_exp_f32_e32 v101, v101
	global_load_lds_dwordx4 v198, s[72:73]
	s_add_u32 s72, s72, 0x90000
	s_addc_u32 s73, s73, 0
	s_add_i32 m0, s68, 16384
	v_exp_f32_e32 v102, v102
	v_exp_f32_e32 v103, v103
	v_exp_f32_e32 v104, v104
	global_load_lds_dwordx4 v199, s[70:71]
	s_add_i32 m0, s68, 24576
	v_exp_f32_e32 v105, v105
	v_exp_f32_e32 v106, v106
	v_exp_f32_e32 v107, v107
	global_load_lds_dwordx4 v219, s[70:71]
	s_add_u32 s70, s70, 0x90000
	s_addc_u32 s71, s71, 0
	ds_read_b128 v[236:239], v206 offset:0
	ds_read_b128 v[240:243], v206 offset:2048
	ds_read_b128 v[244:247], v206 offset:4096
	ds_read_b128 v[190:193], v206 offset:6144
	ds_read_b128 v[194:197], v206 offset:8192
	v_exp_f32_e32 v108, v108
	v_exp_f32_e32 v109, v109
	v_exp_f32_e32 v110, v110
	v_exp_f32_e32 v111, v111
	v_exp_f32_e32 v112, v112
	v_exp_f32_e32 v113, v113
	v_exp_f32_e32 v114, v114
	v_exp_f32_e32 v115, v115
	v_exp_f32_e32 v116, v116
	v_exp_f32_e32 v117, v117
	v_exp_f32_e32 v118, v118
	v_exp_f32_e32 v119, v119
	v_exp_f32_e32 v120, v120
	v_exp_f32_e32 v121, v121
	v_exp_f32_e32 v122, v122
	v_exp_f32_e32 v123, v123
	v_exp_f32_e32 v124, v124
	v_exp_f32_e32 v125, v125
	v_exp_f32_e32 v126, v126
	v_exp_f32_e32 v127, v127
	v_cvt_pk_bf16_f32 v220, v96, v97
	v_cvt_pk_bf16_f32 v221, v98, v99
	v_cvt_pk_bf16_f32 v222, v100, v101
	v_cvt_pk_bf16_f32 v223, v102, v103
	v_add_f32_e32 v218, v96, v218
	v_add_f32_e32 v248, v97, v248
	v_add_f32_e32 v218, v98, v218
	v_add_f32_e32 v248, v99, v248
	v_add_f32_e32 v218, v100, v218
	v_add_f32_e32 v248, v101, v248
	v_add_f32_e32 v218, v102, v218
	v_add_f32_e32 v248, v103, v248
	v_cvt_pk_bf16_f32 v224, v104, v105
	v_cvt_pk_bf16_f32 v225, v106, v107
	v_cvt_pk_bf16_f32 v226, v108, v109
	v_cvt_pk_bf16_f32 v227, v110, v111
	v_add_f32_e32 v218, v104, v218
	v_add_f32_e32 v248, v105, v248
	v_add_f32_e32 v218, v106, v218
	v_add_f32_e32 v248, v107, v248
	v_add_f32_e32 v218, v108, v218
	v_add_f32_e32 v248, v109, v248
	v_add_f32_e32 v218, v110, v218
	v_add_f32_e32 v248, v111, v248
	v_cvt_pk_bf16_f32 v228, v112, v113
	v_cvt_pk_bf16_f32 v229, v114, v115
	v_cvt_pk_bf16_f32 v230, v116, v117
	v_cvt_pk_bf16_f32 v231, v118, v119
	v_add_f32_e32 v249, v112, v249
	v_add_f32_e32 v251, v113, v251
	v_add_f32_e32 v249, v114, v249
	v_add_f32_e32 v251, v115, v251
	v_add_f32_e32 v249, v116, v249
	v_add_f32_e32 v251, v117, v251
	v_add_f32_e32 v249, v118, v249
	v_add_f32_e32 v251, v119, v251
	v_cvt_pk_bf16_f32 v232, v120, v121
	v_cvt_pk_bf16_f32 v233, v122, v123
	v_cvt_pk_bf16_f32 v234, v124, v125
	v_cvt_pk_bf16_f32 v235, v126, v127
	v_add_f32_e32 v249, v120, v249
	v_add_f32_e32 v251, v121, v251
	v_add_f32_e32 v249, v122, v249
	v_add_f32_e32 v251, v123, v251
	v_add_f32_e32 v249, v124, v249
	v_add_f32_e32 v251, v125, v251
	v_add_f32_e32 v249, v126, v249
	v_add_f32_e32 v251, v127, v251
	s_waitcnt vmcnt(4)
	s_barrier
	s_setprio 1
	s_waitcnt lgkmcnt(4)
	v_mfma_f32_32x32x16_bf16 v[96:111], v[236:239], v[172:175], v[16:31]
	ds_read_b128 v[252:255], v206 offset:10240
	s_waitcnt lgkmcnt(4)
	v_mfma_f32_32x32x16_bf16 v[96:111], v[240:243], v[168:171], v[96:111]
	ds_read_b128 v[236:239], v206 offset:12288
	s_waitcnt lgkmcnt(4)
	v_mfma_f32_32x32x16_bf16 v[96:111], v[244:247], v[164:167], v[96:111]
	ds_read_b128 v[240:243], v206 offset:14336
	s_waitcnt lgkmcnt(4)
	v_mfma_f32_32x32x16_bf16 v[96:111], v[190:193], v[160:163], v[96:111]
	ds_read_b128 v[244:247], v206 offset:1024
	s_waitcnt lgkmcnt(4)
	v_mfma_f32_32x32x16_bf16 v[96:111], v[194:197], v[156:159], v[96:111]
	ds_read_b128 v[190:193], v206 offset:3072
	s_waitcnt lgkmcnt(4)
	v_mfma_f32_32x32x16_bf16 v[96:111], v[252:255], v[152:155], v[96:111]
	ds_read_b128 v[194:197], v206 offset:5120
	s_waitcnt lgkmcnt(4)
	v_mfma_f32_32x32x16_bf16 v[96:111], v[236:239], v[148:151], v[96:111]
	ds_read_b128 v[252:255], v206 offset:7168
	s_waitcnt lgkmcnt(4)
	v_mfma_f32_32x32x16_bf16 v[96:111], v[240:243], v[144:147], v[96:111]
	ds_read_b128 v[236:239], v206 offset:9216
	s_waitcnt lgkmcnt(4)
	v_mfma_f32_32x32x16_bf16 v[112:127], v[244:247], v[172:175], v[16:31]
	ds_read_b128 v[240:243], v206 offset:11264
	s_waitcnt lgkmcnt(4)
	v_mfma_f32_32x32x16_bf16 v[112:127], v[190:193], v[168:171], v[112:127]
	ds_read_b128 v[244:247], v206 offset:13312
	s_waitcnt lgkmcnt(4)
	v_mfma_f32_32x32x16_bf16 v[112:127], v[194:197], v[164:167], v[112:127]
	ds_read_b128 v[190:193], v206 offset:15360
	s_waitcnt lgkmcnt(4)
	v_mfma_f32_32x32x16_bf16 v[112:127], v[252:255], v[160:163], v[112:127]
	ds_read_b64_tr_b16 v[194:195], v201 offset:49152
	ds_read_b64_tr_b16 v[196:197], v201 offset:51200
	s_waitcnt lgkmcnt(5)
	v_mfma_f32_32x32x16_bf16 v[112:127], v[236:239], v[156:159], v[112:127]
	ds_read_b64_tr_b16 v[252:253], v201 offset:53248
	ds_read_b64_tr_b16 v[254:255], v201 offset:55296
	s_waitcnt lgkmcnt(6)
	v_mfma_f32_32x32x16_bf16 v[112:127], v[240:243], v[152:155], v[112:127]
	ds_read_b64_tr_b16 v[236:237], v201 offset:57344
	ds_read_b64_tr_b16 v[238:239], v201 offset:59392
	s_waitcnt lgkmcnt(7)
	v_mfma_f32_32x32x16_bf16 v[112:127], v[244:247], v[148:151], v[112:127]
	ds_read_b64_tr_b16 v[240:241], v201 offset:61440
	ds_read_b64_tr_b16 v[242:243], v201 offset:63488
	s_waitcnt lgkmcnt(8)
	v_mfma_f32_32x32x16_bf16 v[112:127], v[190:193], v[144:147], v[112:127]
	ds_read_b64_tr_b16 v[244:245], v201 offset:49664
	ds_read_b64_tr_b16 v[246:247], v201 offset:51712
	s_waitcnt lgkmcnt(8)
	v_mfma_f32_32x32x16_bf16 v[80:95], v[220:223], v[194:197], v[80:95]
	ds_read_b64_tr_b16 v[190:191], v201 offset:53760
	ds_read_b64_tr_b16 v[192:193], v201 offset:55808
	s_waitcnt lgkmcnt(8)
	v_mfma_f32_32x32x16_bf16 v[80:95], v[224:227], v[252:255], v[80:95]
	ds_read_b64_tr_b16 v[194:195], v201 offset:57856
	ds_read_b64_tr_b16 v[196:197], v201 offset:59904
	s_waitcnt lgkmcnt(8)
	v_mfma_f32_32x32x16_bf16 v[80:95], v[228:231], v[236:239], v[80:95]
	ds_read_b64_tr_b16 v[252:253], v201 offset:61952
	ds_read_b64_tr_b16 v[254:255], v201 offset:64000
	s_waitcnt lgkmcnt(8)
	v_mfma_f32_32x32x16_bf16 v[80:95], v[232:235], v[240:243], v[80:95]
	ds_read_b64_tr_b16 v[236:237], v201 offset:50176
	ds_read_b64_tr_b16 v[238:239], v201 offset:52224
	s_waitcnt lgkmcnt(8)
	v_mfma_f32_32x32x16_bf16 v[64:79], v[220:223], v[244:247], v[64:79]
	ds_read_b64_tr_b16 v[240:241], v201 offset:54272
	ds_read_b64_tr_b16 v[242:243], v201 offset:56320
	s_waitcnt lgkmcnt(8)
	v_mfma_f32_32x32x16_bf16 v[64:79], v[224:227], v[190:193], v[64:79]
	ds_read_b64_tr_b16 v[244:245], v201 offset:58368
	ds_read_b64_tr_b16 v[246:247], v201 offset:60416
	s_waitcnt lgkmcnt(8)
	v_mfma_f32_32x32x16_bf16 v[64:79], v[228:231], v[194:197], v[64:79]
	ds_read_b64_tr_b16 v[190:191], v201 offset:62464
	ds_read_b64_tr_b16 v[192:193], v201 offset:64512
	s_waitcnt lgkmcnt(8)
	v_mfma_f32_32x32x16_bf16 v[64:79], v[232:235], v[252:255], v[64:79]
	ds_read_b64_tr_b16 v[194:195], v201 offset:50688
	ds_read_b64_tr_b16 v[196:197], v201 offset:52736
	s_waitcnt lgkmcnt(8)
	v_mfma_f32_32x32x16_bf16 v[48:63], v[220:223], v[236:239], v[48:63]
	ds_read_b64_tr_b16 v[252:253], v201 offset:54784
	ds_read_b64_tr_b16 v[254:255], v201 offset:56832
	s_waitcnt lgkmcnt(8)
	v_mfma_f32_32x32x16_bf16 v[48:63], v[224:227], v[240:243], v[48:63]
	ds_read_b64_tr_b16 v[236:237], v201 offset:58880
	ds_read_b64_tr_b16 v[238:239], v201 offset:60928
	s_waitcnt lgkmcnt(8)
	v_mfma_f32_32x32x16_bf16 v[48:63], v[228:231], v[244:247], v[48:63]
	ds_read_b64_tr_b16 v[240:241], v201 offset:62976
	ds_read_b64_tr_b16 v[242:243], v201 offset:65024
	s_waitcnt lgkmcnt(8)
	v_mfma_f32_32x32x16_bf16 v[48:63], v[232:235], v[190:193], v[48:63]
	s_waitcnt lgkmcnt(6)
	v_mfma_f32_32x32x16_bf16 v[32:47], v[220:223], v[194:197], v[32:47]
	s_waitcnt lgkmcnt(4)
	v_mfma_f32_32x32x16_bf16 v[32:47], v[224:227], v[252:255], v[32:47]
	s_waitcnt lgkmcnt(2)
	v_mfma_f32_32x32x16_bf16 v[32:47], v[228:231], v[236:239], v[32:47]
	s_waitcnt lgkmcnt(0)
	v_mfma_f32_32x32x16_bf16 v[32:47], v[232:235], v[240:243], v[32:47]
	s_setprio 0
	s_waitcnt vmcnt(4) lgkmcnt(0)
	s_barrier
	s_add_i32 m0, s74, 49152
	v_exp_f32_e32 v96, v96
	v_exp_f32_e32 v97, v97
	v_exp_f32_e32 v98, v98
	global_load_lds_dwordx4 v180, s[72:73]
	s_add_i32 m0, s74, 57344
	v_exp_f32_e32 v99, v99
	v_exp_f32_e32 v100, v100
	v_exp_f32_e32 v101, v101
	global_load_lds_dwordx4 v198, s[72:73]
	s_add_u32 s72, s72, 0x90000
	s_addc_u32 s73, s73, 0
	s_add_i32 m0, s68, 32768
	v_exp_f32_e32 v102, v102
	v_exp_f32_e32 v103, v103
	v_exp_f32_e32 v104, v104
	global_load_lds_dwordx4 v199, s[70:71]
	s_add_i32 m0, s68, 40960
	v_exp_f32_e32 v105, v105
	v_exp_f32_e32 v106, v106
	v_exp_f32_e32 v107, v107
	global_load_lds_dwordx4 v219, s[70:71]
	s_add_u32 s70, s70, 0x90000
	s_addc_u32 s71, s71, 0
	ds_read_b128 v[236:239], v206 offset:16384
	ds_read_b128 v[240:243], v206 offset:18432
	ds_read_b128 v[244:247], v206 offset:20480
	ds_read_b128 v[190:193], v206 offset:22528
	ds_read_b128 v[194:197], v206 offset:24576
	v_exp_f32_e32 v108, v108
	v_exp_f32_e32 v109, v109
	v_exp_f32_e32 v110, v110
	v_exp_f32_e32 v111, v111
	v_exp_f32_e32 v112, v112
	v_exp_f32_e32 v113, v113
	v_exp_f32_e32 v114, v114
	v_exp_f32_e32 v115, v115
	v_exp_f32_e32 v116, v116
	v_exp_f32_e32 v117, v117
	v_exp_f32_e32 v118, v118
	v_exp_f32_e32 v119, v119
	v_exp_f32_e32 v120, v120
	v_exp_f32_e32 v121, v121
	v_exp_f32_e32 v122, v122
	v_exp_f32_e32 v123, v123
	v_exp_f32_e32 v124, v124
	v_exp_f32_e32 v125, v125
	v_exp_f32_e32 v126, v126
	v_exp_f32_e32 v127, v127
	v_cvt_pk_bf16_f32 v220, v96, v97
	v_cvt_pk_bf16_f32 v221, v98, v99
	v_cvt_pk_bf16_f32 v222, v100, v101
	v_cvt_pk_bf16_f32 v223, v102, v103
	v_add_f32_e32 v218, v96, v218
	v_add_f32_e32 v248, v97, v248
	v_add_f32_e32 v218, v98, v218
	v_add_f32_e32 v248, v99, v248
	v_add_f32_e32 v218, v100, v218
	v_add_f32_e32 v248, v101, v248
	v_add_f32_e32 v218, v102, v218
	v_add_f32_e32 v248, v103, v248
	v_cvt_pk_bf16_f32 v224, v104, v105
	v_cvt_pk_bf16_f32 v225, v106, v107
	v_cvt_pk_bf16_f32 v226, v108, v109
	v_cvt_pk_bf16_f32 v227, v110, v111
	v_add_f32_e32 v218, v104, v218
	v_add_f32_e32 v248, v105, v248
	v_add_f32_e32 v218, v106, v218
	v_add_f32_e32 v248, v107, v248
	v_add_f32_e32 v218, v108, v218
	v_add_f32_e32 v248, v109, v248
	v_add_f32_e32 v218, v110, v218
	v_add_f32_e32 v248, v111, v248
	v_cvt_pk_bf16_f32 v228, v112, v113
	v_cvt_pk_bf16_f32 v229, v114, v115
	v_cvt_pk_bf16_f32 v230, v116, v117
	v_cvt_pk_bf16_f32 v231, v118, v119
	v_add_f32_e32 v249, v112, v249
	v_add_f32_e32 v251, v113, v251
	v_add_f32_e32 v249, v114, v249
	v_add_f32_e32 v251, v115, v251
	v_add_f32_e32 v249, v116, v249
	v_add_f32_e32 v251, v117, v251
	v_add_f32_e32 v249, v118, v249
	v_add_f32_e32 v251, v119, v251
	v_cvt_pk_bf16_f32 v232, v120, v121
	v_cvt_pk_bf16_f32 v233, v122, v123
	v_cvt_pk_bf16_f32 v234, v124, v125
	v_cvt_pk_bf16_f32 v235, v126, v127
	v_add_f32_e32 v249, v120, v249
	v_add_f32_e32 v251, v121, v251
	v_add_f32_e32 v249, v122, v249
	v_add_f32_e32 v251, v123, v251
	v_add_f32_e32 v249, v124, v249
	v_add_f32_e32 v251, v125, v251
	v_add_f32_e32 v249, v126, v249
	v_add_f32_e32 v251, v127, v251
	s_waitcnt vmcnt(4)
	s_barrier
	s_sub_u32 s98, s98, 1
	s_cmp_lg_u32 s98, 0
	s_cbranch_scc1 .Lattn_loop
	s_setprio 1
	s_waitcnt lgkmcnt(4)
	v_mfma_f32_32x32x16_bf16 v[96:111], v[236:239], v[172:175], v[16:31]
	ds_read_b128 v[252:255], v206 offset:26624
	s_waitcnt lgkmcnt(4)
	v_mfma_f32_32x32x16_bf16 v[96:111], v[240:243], v[168:171], v[96:111]
	ds_read_b128 v[236:239], v206 offset:28672
	s_waitcnt lgkmcnt(4)
	v_mfma_f32_32x32x16_bf16 v[96:111], v[244:247], v[164:167], v[96:111]
	ds_read_b128 v[240:243], v206 offset:30720
	s_waitcnt lgkmcnt(4)
	v_mfma_f32_32x32x16_bf16 v[96:111], v[190:193], v[160:163], v[96:111]
	ds_read_b128 v[244:247], v206 offset:17408
	s_waitcnt lgkmcnt(4)
	v_mfma_f32_32x32x16_bf16 v[96:111], v[194:197], v[156:159], v[96:111]
	ds_read_b128 v[190:193], v206 offset:19456
	s_waitcnt lgkmcnt(4)
	v_mfma_f32_32x32x16_bf16 v[96:111], v[252:255], v[152:155], v[96:111]
	ds_read_b128 v[194:197], v206 offset:21504
	s_waitcnt lgkmcnt(4)
	v_mfma_f32_32x32x16_bf16 v[96:111], v[236:239], v[148:151], v[96:111]
	ds_read_b128 v[252:255], v206 offset:23552
	s_waitcnt lgkmcnt(4)
	v_mfma_f32_32x32x16_bf16 v[96:111], v[240:243], v[144:147], v[96:111]
	ds_read_b128 v[236:239], v206 offset:25600
	s_waitcnt lgkmcnt(4)
	v_mfma_f32_32x32x16_bf16 v[112:127], v[244:247], v[172:175], v[16:31]
	ds_read_b128 v[240:243], v206 offset:27648
	s_waitcnt lgkmcnt(4)
	v_mfma_f32_32x32x16_bf16 v[112:127], v[190:193], v[168:171], v[112:127]
	ds_read_b128 v[244:247], v206 offset:29696
	s_waitcnt lgkmcnt(4)
	v_mfma_f32_32x32x16_bf16 v[112:127], v[194:197], v[164:167], v[112:127]
	ds_read_b128 v[190:193], v206 offset:31744
	s_waitcnt lgkmcnt(4)
	v_mfma_f32_32x32x16_bf16 v[112:127], v[252:255], v[160:163], v[112:127]
	ds_read_b64_tr_b16 v[194:195], v201 offset:0
	ds_read_b64_tr_b16 v[196:197], v201 offset:2048
	s_waitcnt lgkmcnt(5)
	v_mfma_f32_32x32x16_bf16 v[112:127], v[236:239], v[156:159], v[112:127]
	ds_read_b64_tr_b16 v[252:253], v201 offset:4096
	ds_read_b64_tr_b16 v[254:255], v201 offset:6144
	s_waitcnt lgkmcnt(6)
	v_mfma_f32_32x32x16_bf16 v[112:127], v[240:243], v[152:155], v[112:127]
	ds_read_b64_tr_b16 v[236:237], v201 offset:8192
	ds_read_b64_tr_b16 v[238:239], v201 offset:10240
	s_waitcnt lgkmcnt(7)
	v_mfma_f32_32x32x16_bf16 v[112:127], v[244:247], v[148:151], v[112:127]
	ds_read_b64_tr_b16 v[240:241], v201 offset:12288
	ds_read_b64_tr_b16 v[242:243], v201 offset:14336
	s_waitcnt lgkmcnt(8)
	v_mfma_f32_32x32x16_bf16 v[112:127], v[190:193], v[144:147], v[112:127]
	ds_read_b64_tr_b16 v[244:245], v201 offset:512
	ds_read_b64_tr_b16 v[246:247], v201 offset:2560
	s_waitcnt lgkmcnt(8)
	v_mfma_f32_32x32x16_bf16 v[80:95], v[220:223], v[194:197], v[80:95]
	ds_read_b64_tr_b16 v[190:191], v201 offset:4608
	ds_read_b64_tr_b16 v[192:193], v201 offset:6656
	s_waitcnt lgkmcnt(8)
	v_mfma_f32_32x32x16_bf16 v[80:95], v[224:227], v[252:255], v[80:95]
	ds_read_b64_tr_b16 v[194:195], v201 offset:8704
	ds_read_b64_tr_b16 v[196:197], v201 offset:10752
	s_waitcnt lgkmcnt(8)
	v_mfma_f32_32x32x16_bf16 v[80:95], v[228:231], v[236:239], v[80:95]
	ds_read_b64_tr_b16 v[252:253], v201 offset:12800
	ds_read_b64_tr_b16 v[254:255], v201 offset:14848
	s_waitcnt lgkmcnt(8)
	v_mfma_f32_32x32x16_bf16 v[80:95], v[232:235], v[240:243], v[80:95]
	ds_read_b64_tr_b16 v[236:237], v201 offset:1024
	ds_read_b64_tr_b16 v[238:239], v201 offset:3072
	s_waitcnt lgkmcnt(8)
	v_mfma_f32_32x32x16_bf16 v[64:79], v[220:223], v[244:247], v[64:79]
	ds_read_b64_tr_b16 v[240:241], v201 offset:5120
	ds_read_b64_tr_b16 v[242:243], v201 offset:7168
	s_waitcnt lgkmcnt(8)
	v_mfma_f32_32x32x16_bf16 v[64:79], v[224:227], v[190:193], v[64:79]
	ds_read_b64_tr_b16 v[244:245], v201 offset:9216
	ds_read_b64_tr_b16 v[246:247], v201 offset:11264
	s_waitcnt lgkmcnt(8)
	v_mfma_f32_32x32x16_bf16 v[64:79], v[228:231], v[194:197], v[64:79]
	ds_read_b64_tr_b16 v[190:191], v201 offset:13312
	ds_read_b64_tr_b16 v[192:193], v201 offset:15360
	s_waitcnt lgkmcnt(8)
	v_mfma_f32_32x32x16_bf16 v[64:79], v[232:235], v[252:255], v[64:79]
	ds_read_b64_tr_b16 v[194:195], v201 offset:1536
	ds_read_b64_tr_b16 v[196:197], v201 offset:3584
	s_waitcnt lgkmcnt(8)
	v_mfma_f32_32x32x16_bf16 v[48:63], v[220:223], v[236:239], v[48:63]
	ds_read_b64_tr_b16 v[252:253], v201 offset:5632
	ds_read_b64_tr_b16 v[254:255], v201 offset:7680
	s_waitcnt lgkmcnt(8)
	v_mfma_f32_32x32x16_bf16 v[48:63], v[224:227], v[240:243], v[48:63]
	ds_read_b64_tr_b16 v[236:237], v201 offset:9728
	ds_read_b64_tr_b16 v[238:239], v201 offset:11776
	s_waitcnt lgkmcnt(8)
	v_mfma_f32_32x32x16_bf16 v[48:63], v[228:231], v[244:247], v[48:63]
	ds_read_b64_tr_b16 v[240:241], v201 offset:13824
	ds_read_b64_tr_b16 v[242:243], v201 offset:15872
	s_waitcnt lgkmcnt(8)
	v_mfma_f32_32x32x16_bf16 v[48:63], v[232:235], v[190:193], v[48:63]
	s_waitcnt lgkmcnt(6)
	v_mfma_f32_32x32x16_bf16 v[32:47], v[220:223], v[194:197], v[32:47]
	s_waitcnt lgkmcnt(4)
	v_mfma_f32_32x32x16_bf16 v[32:47], v[224:227], v[252:255], v[32:47]
	s_waitcnt lgkmcnt(2)
	v_mfma_f32_32x32x16_bf16 v[32:47], v[228:231], v[236:239], v[32:47]
	s_waitcnt lgkmcnt(0)
	v_mfma_f32_32x32x16_bf16 v[32:47], v[232:235], v[240:243], v[32:47]
	s_setprio 0
	s_waitcnt vmcnt(4) lgkmcnt(0)
	s_barrier
	s_add_i32 m0, s68, 49152
	v_exp_f32_e32 v96, v96
	v_exp_f32_e32 v97, v97
	v_exp_f32_e32 v98, v98
	global_load_lds_dwordx4 v199, s[70:71]
	s_add_i32 m0, s68, 57344
	v_exp_f32_e32 v99, v99
	v_exp_f32_e32 v100, v100
	v_exp_f32_e32 v101, v101
	global_load_lds_dwordx4 v219, s[70:71]
	s_add_u32 s70, s70, 0x90000
	s_addc_u32 s71, s71, 0
	ds_read_b128 v[236:239], v206 offset:32768
	ds_read_b128 v[240:243], v206 offset:34816
	ds_read_b128 v[244:247], v206 offset:36864
	ds_read_b128 v[190:193], v206 offset:38912
	ds_read_b128 v[194:197], v206 offset:40960
	v_exp_f32_e32 v102, v102
	v_exp_f32_e32 v103, v103
	v_exp_f32_e32 v104, v104
	v_exp_f32_e32 v105, v105
	v_exp_f32_e32 v106, v106
	v_exp_f32_e32 v107, v107
	v_exp_f32_e32 v108, v108
	v_exp_f32_e32 v109, v109
	v_exp_f32_e32 v110, v110
	v_exp_f32_e32 v111, v111
	v_exp_f32_e32 v112, v112
	v_exp_f32_e32 v113, v113
	v_exp_f32_e32 v114, v114
	v_exp_f32_e32 v115, v115
	v_exp_f32_e32 v116, v116
	v_exp_f32_e32 v117, v117
	v_exp_f32_e32 v118, v118
	v_exp_f32_e32 v119, v119
	v_exp_f32_e32 v120, v120
	v_exp_f32_e32 v121, v121
	v_exp_f32_e32 v122, v122
	v_exp_f32_e32 v123, v123
	v_exp_f32_e32 v124, v124
	v_exp_f32_e32 v125, v125
	v_exp_f32_e32 v126, v126
	v_exp_f32_e32 v127, v127
	v_cvt_pk_bf16_f32 v220, v96, v97
	v_cvt_pk_bf16_f32 v221, v98, v99
	v_cvt_pk_bf16_f32 v222, v100, v101
	v_cvt_pk_bf16_f32 v223, v102, v103
	v_add_f32_e32 v218, v96, v218
	v_add_f32_e32 v248, v97, v248
	v_add_f32_e32 v218, v98, v218
	v_add_f32_e32 v248, v99, v248
	v_add_f32_e32 v218, v100, v218
	v_add_f32_e32 v248, v101, v248
	v_add_f32_e32 v218, v102, v218
	v_add_f32_e32 v248, v103, v248
	v_cvt_pk_bf16_f32 v224, v104, v105
	v_cvt_pk_bf16_f32 v225, v106, v107
	v_cvt_pk_bf16_f32 v226, v108, v109
	v_cvt_pk_bf16_f32 v227, v110, v111
	v_add_f32_e32 v218, v104, v218
	v_add_f32_e32 v248, v105, v248
	v_add_f32_e32 v218, v106, v218
	v_add_f32_e32 v248, v107, v248
	v_add_f32_e32 v218, v108, v218
	v_add_f32_e32 v248, v109, v248
	v_add_f32_e32 v218, v110, v218
	v_add_f32_e32 v248, v111, v248
	v_cvt_pk_bf16_f32 v228, v112, v113
	v_cvt_pk_bf16_f32 v229, v114, v115
	v_cvt_pk_bf16_f32 v230, v116, v117
	v_cvt_pk_bf16_f32 v231, v118, v119
	v_add_f32_e32 v249, v112, v249
	v_add_f32_e32 v251, v113, v251
	v_add_f32_e32 v249, v114, v249
	v_add_f32_e32 v251, v115, v251
	v_add_f32_e32 v249, v116, v249
	v_add_f32_e32 v251, v117, v251
	v_add_f32_e32 v249, v118, v249
	v_add_f32_e32 v251, v119, v251
	v_cvt_pk_bf16_f32 v232, v120, v121
	v_cvt_pk_bf16_f32 v233, v122, v123
	v_cvt_pk_bf16_f32 v234, v124, v125
	v_cvt_pk_bf16_f32 v235, v126, v127
	v_add_f32_e32 v249, v120, v249
	v_add_f32_e32 v251, v121, v251
	v_add_f32_e32 v249, v122, v249
	v_add_f32_e32 v251, v123, v251
	v_add_f32_e32 v249, v124, v249
	v_add_f32_e32 v251, v125, v251
	v_add_f32_e32 v249, v126, v249
	v_add_f32_e32 v251, v127, v251
	s_waitcnt vmcnt(2)
	s_barrier
	s_setprio 1
	s_waitcnt lgkmcnt(4)
	v_mfma_f32_32x32x16_bf16 v[96:111], v[236:239], v[172:175], v[16:31]
	ds_read_b128 v[252:255], v206 offset:43008
	s_waitcnt lgkmcnt(4)
	v_mfma_f32_32x32x16_bf16 v[96:111], v[240:243], v[168:171], v[96:111]
	ds_read_b128 v[236:239], v206 offset:45056
	s_waitcnt lgkmcnt(4)
	v_mfma_f32_32x32x16_bf16 v[96:111], v[244:247], v[164:167], v[96:111]
	ds_read_b128 v[240:243], v206 offset:47104
	s_waitcnt lgkmcnt(4)
	v_mfma_f32_32x32x16_bf16 v[96:111], v[190:193], v[160:163], v[96:111]
	ds_read_b128 v[244:247], v206 offset:33792
	s_waitcnt lgkmcnt(4)
	v_mfma_f32_32x32x16_bf16 v[96:111], v[194:197], v[156:159], v[96:111]
	ds_read_b128 v[190:193], v206 offset:35840
	s_waitcnt lgkmcnt(4)
	v_mfma_f32_32x32x16_bf16 v[96:111], v[252:255], v[152:155], v[96:111]
	ds_read_b128 v[194:197], v206 offset:37888
	s_waitcnt lgkmcnt(4)
	v_mfma_f32_32x32x16_bf16 v[96:111], v[236:239], v[148:151], v[96:111]
	ds_read_b128 v[252:255], v206 offset:39936
	s_waitcnt lgkmcnt(4)
	v_mfma_f32_32x32x16_bf16 v[96:111], v[240:243], v[144:147], v[96:111]
	ds_read_b128 v[236:239], v206 offset:41984
	s_waitcnt lgkmcnt(4)
	v_mfma_f32_32x32x16_bf16 v[112:127], v[244:247], v[172:175], v[16:31]
	ds_read_b128 v[240:243], v206 offset:44032
	s_waitcnt lgkmcnt(4)
	v_mfma_f32_32x32x16_bf16 v[112:127], v[190:193], v[168:171], v[112:127]
	ds_read_b128 v[244:247], v206 offset:46080
	s_waitcnt lgkmcnt(4)
	v_mfma_f32_32x32x16_bf16 v[112:127], v[194:197], v[164:167], v[112:127]
	ds_read_b128 v[190:193], v206 offset:48128
	s_waitcnt lgkmcnt(4)
	v_mfma_f32_32x32x16_bf16 v[112:127], v[252:255], v[160:163], v[112:127]
	ds_read_b64_tr_b16 v[194:195], v201 offset:16384
	ds_read_b64_tr_b16 v[196:197], v201 offset:18432
	s_waitcnt lgkmcnt(5)
	v_mfma_f32_32x32x16_bf16 v[112:127], v[236:239], v[156:159], v[112:127]
	ds_read_b64_tr_b16 v[252:253], v201 offset:20480
	ds_read_b64_tr_b16 v[254:255], v201 offset:22528
	s_waitcnt lgkmcnt(6)
	v_mfma_f32_32x32x16_bf16 v[112:127], v[240:243], v[152:155], v[112:127]
	ds_read_b64_tr_b16 v[236:237], v201 offset:24576
	ds_read_b64_tr_b16 v[238:239], v201 offset:26624
	s_waitcnt lgkmcnt(7)
	v_mfma_f32_32x32x16_bf16 v[112:127], v[244:247], v[148:151], v[112:127]
	ds_read_b64_tr_b16 v[240:241], v201 offset:28672
	ds_read_b64_tr_b16 v[242:243], v201 offset:30720
	s_waitcnt lgkmcnt(8)
	v_mfma_f32_32x32x16_bf16 v[112:127], v[190:193], v[144:147], v[112:127]
	ds_read_b64_tr_b16 v[244:245], v201 offset:16896
	ds_read_b64_tr_b16 v[246:247], v201 offset:18944
	s_waitcnt lgkmcnt(8)
	v_mfma_f32_32x32x16_bf16 v[80:95], v[220:223], v[194:197], v[80:95]
	ds_read_b64_tr_b16 v[190:191], v201 offset:20992
	ds_read_b64_tr_b16 v[192:193], v201 offset:23040
	s_waitcnt lgkmcnt(8)
	v_mfma_f32_32x32x16_bf16 v[80:95], v[224:227], v[252:255], v[80:95]
	ds_read_b64_tr_b16 v[194:195], v201 offset:25088
	ds_read_b64_tr_b16 v[196:197], v201 offset:27136
	s_waitcnt lgkmcnt(8)
	v_mfma_f32_32x32x16_bf16 v[80:95], v[228:231], v[236:239], v[80:95]
	ds_read_b64_tr_b16 v[252:253], v201 offset:29184
	ds_read_b64_tr_b16 v[254:255], v201 offset:31232
	s_waitcnt lgkmcnt(8)
	v_mfma_f32_32x32x16_bf16 v[80:95], v[232:235], v[240:243], v[80:95]
	ds_read_b64_tr_b16 v[236:237], v201 offset:17408
	ds_read_b64_tr_b16 v[238:239], v201 offset:19456
	s_waitcnt lgkmcnt(8)
	v_mfma_f32_32x32x16_bf16 v[64:79], v[220:223], v[244:247], v[64:79]
	ds_read_b64_tr_b16 v[240:241], v201 offset:21504
	ds_read_b64_tr_b16 v[242:243], v201 offset:23552
	s_waitcnt lgkmcnt(8)
	v_mfma_f32_32x32x16_bf16 v[64:79], v[224:227], v[190:193], v[64:79]
	ds_read_b64_tr_b16 v[244:245], v201 offset:25600
	ds_read_b64_tr_b16 v[246:247], v201 offset:27648
	s_waitcnt lgkmcnt(8)
	v_mfma_f32_32x32x16_bf16 v[64:79], v[228:231], v[194:197], v[64:79]
	ds_read_b64_tr_b16 v[190:191], v201 offset:29696
	ds_read_b64_tr_b16 v[192:193], v201 offset:31744
	s_waitcnt lgkmcnt(8)
	v_mfma_f32_32x32x16_bf16 v[64:79], v[232:235], v[252:255], v[64:79]
	ds_read_b64_tr_b16 v[194:195], v201 offset:17920
	ds_read_b64_tr_b16 v[196:197], v201 offset:19968
	s_waitcnt lgkmcnt(8)
	v_mfma_f32_32x32x16_bf16 v[48:63], v[220:223], v[236:239], v[48:63]
	ds_read_b64_tr_b16 v[252:253], v201 offset:22016
	ds_read_b64_tr_b16 v[254:255], v201 offset:24064
	s_waitcnt lgkmcnt(8)
	v_mfma_f32_32x32x16_bf16 v[48:63], v[224:227], v[240:243], v[48:63]
	ds_read_b64_tr_b16 v[236:237], v201 offset:26112
	ds_read_b64_tr_b16 v[238:239], v201 offset:28160
	s_waitcnt lgkmcnt(8)
	v_mfma_f32_32x32x16_bf16 v[48:63], v[228:231], v[244:247], v[48:63]
	ds_read_b64_tr_b16 v[240:241], v201 offset:30208
	ds_read_b64_tr_b16 v[242:243], v201 offset:32256
	s_waitcnt lgkmcnt(8)
	v_mfma_f32_32x32x16_bf16 v[48:63], v[232:235], v[190:193], v[48:63]
	s_waitcnt lgkmcnt(6)
	v_mfma_f32_32x32x16_bf16 v[32:47], v[220:223], v[194:197], v[32:47]
	s_waitcnt lgkmcnt(4)
	v_mfma_f32_32x32x16_bf16 v[32:47], v[224:227], v[252:255], v[32:47]
	s_waitcnt lgkmcnt(2)
	v_mfma_f32_32x32x16_bf16 v[32:47], v[228:231], v[236:239], v[32:47]
	s_waitcnt lgkmcnt(0)
	v_mfma_f32_32x32x16_bf16 v[32:47], v[232:235], v[240:243], v[32:47]
	s_setprio 0
	s_waitcnt vmcnt(2) lgkmcnt(0)
	s_barrier
	ds_read_b128 v[236:239], v206 offset:49152
	ds_read_b128 v[240:243], v206 offset:51200
	ds_read_b128 v[244:247], v206 offset:53248
	ds_read_b128 v[190:193], v206 offset:55296
	ds_read_b128 v[194:197], v206 offset:57344
	v_exp_f32_e32 v96, v96
	v_exp_f32_e32 v97, v97
	v_exp_f32_e32 v98, v98
	v_exp_f32_e32 v99, v99
	v_exp_f32_e32 v100, v100
	v_exp_f32_e32 v101, v101
	v_exp_f32_e32 v102, v102
	v_exp_f32_e32 v103, v103
	v_exp_f32_e32 v104, v104
	v_exp_f32_e32 v105, v105
	v_exp_f32_e32 v106, v106
	v_exp_f32_e32 v107, v107
	v_exp_f32_e32 v108, v108
	v_exp_f32_e32 v109, v109
	v_exp_f32_e32 v110, v110
	v_exp_f32_e32 v111, v111
	v_exp_f32_e32 v112, v112
	v_exp_f32_e32 v113, v113
	v_exp_f32_e32 v114, v114
	v_exp_f32_e32 v115, v115
	v_exp_f32_e32 v116, v116
	v_exp_f32_e32 v117, v117
	v_exp_f32_e32 v118, v118
	v_exp_f32_e32 v119, v119
	v_exp_f32_e32 v120, v120
	v_exp_f32_e32 v121, v121
	v_exp_f32_e32 v122, v122
	v_exp_f32_e32 v123, v123
	v_exp_f32_e32 v124, v124
	v_exp_f32_e32 v125, v125
	v_exp_f32_e32 v126, v126
	v_exp_f32_e32 v127, v127
	v_cvt_pk_bf16_f32 v220, v96, v97
	v_cvt_pk_bf16_f32 v221, v98, v99
	v_cvt_pk_bf16_f32 v222, v100, v101
	v_cvt_pk_bf16_f32 v223, v102, v103
	v_add_f32_e32 v218, v96, v218
	v_add_f32_e32 v248, v97, v248
	v_add_f32_e32 v218, v98, v218
	v_add_f32_e32 v248, v99, v248
	v_add_f32_e32 v218, v100, v218
	v_add_f32_e32 v248, v101, v248
	v_add_f32_e32 v218, v102, v218
	v_add_f32_e32 v248, v103, v248
	v_cvt_pk_bf16_f32 v224, v104, v105
	v_cvt_pk_bf16_f32 v225, v106, v107
	v_cvt_pk_bf16_f32 v226, v108, v109
	v_cvt_pk_bf16_f32 v227, v110, v111
	v_add_f32_e32 v218, v104, v218
	v_add_f32_e32 v248, v105, v248
	v_add_f32_e32 v218, v106, v218
	v_add_f32_e32 v248, v107, v248
	v_add_f32_e32 v218, v108, v218
	v_add_f32_e32 v248, v109, v248
	v_add_f32_e32 v218, v110, v218
	v_add_f32_e32 v248, v111, v248
	v_cvt_pk_bf16_f32 v228, v112, v113
	v_cvt_pk_bf16_f32 v229, v114, v115
	v_cvt_pk_bf16_f32 v230, v116, v117
	v_cvt_pk_bf16_f32 v231, v118, v119
	v_add_f32_e32 v249, v112, v249
	v_add_f32_e32 v251, v113, v251
	v_add_f32_e32 v249, v114, v249
	v_add_f32_e32 v251, v115, v251
	v_add_f32_e32 v249, v116, v249
	v_add_f32_e32 v251, v117, v251
	v_add_f32_e32 v249, v118, v249
	v_add_f32_e32 v251, v119, v251
	v_cvt_pk_bf16_f32 v232, v120, v121
	v_cvt_pk_bf16_f32 v233, v122, v123
	v_cvt_pk_bf16_f32 v234, v124, v125
	v_cvt_pk_bf16_f32 v235, v126, v127
	v_add_f32_e32 v249, v120, v249
	v_add_f32_e32 v251, v121, v251
	v_add_f32_e32 v249, v122, v249
	v_add_f32_e32 v251, v123, v251
	v_add_f32_e32 v249, v124, v249
	v_add_f32_e32 v251, v125, v251
	v_add_f32_e32 v249, v126, v249
	v_add_f32_e32 v251, v127, v251
	s_waitcnt vmcnt(0)
	s_barrier
	s_setprio 1
	s_waitcnt lgkmcnt(4)
	v_mfma_f32_32x32x16_bf16 v[96:111], v[236:239], v[172:175], v[16:31]
	ds_read_b128 v[252:255], v206 offset:59392
	s_waitcnt lgkmcnt(4)
	v_mfma_f32_32x32x16_bf16 v[96:111], v[240:243], v[168:171], v[96:111]
	ds_read_b128 v[236:239], v206 offset:61440
	s_waitcnt lgkmcnt(4)
	v_mfma_f32_32x32x16_bf16 v[96:111], v[244:247], v[164:167], v[96:111]
	ds_read_b128 v[240:243], v206 offset:63488
	s_waitcnt lgkmcnt(4)
	v_mfma_f32_32x32x16_bf16 v[96:111], v[190:193], v[160:163], v[96:111]
	ds_read_b128 v[244:247], v206 offset:50176
	s_waitcnt lgkmcnt(4)
	v_mfma_f32_32x32x16_bf16 v[96:111], v[194:197], v[156:159], v[96:111]
	ds_read_b128 v[190:193], v206 offset:52224
	s_waitcnt lgkmcnt(4)
	v_mfma_f32_32x32x16_bf16 v[96:111], v[252:255], v[152:155], v[96:111]
	ds_read_b128 v[194:197], v206 offset:54272
	s_waitcnt lgkmcnt(4)
	v_mfma_f32_32x32x16_bf16 v[96:111], v[236:239], v[148:151], v[96:111]
	ds_read_b128 v[252:255], v206 offset:56320
	s_waitcnt lgkmcnt(4)
	v_mfma_f32_32x32x16_bf16 v[96:111], v[240:243], v[144:147], v[96:111]
	ds_read_b128 v[236:239], v206 offset:58368
	s_waitcnt lgkmcnt(4)
	v_mfma_f32_32x32x16_bf16 v[112:127], v[244:247], v[172:175], v[16:31]
	ds_read_b128 v[240:243], v206 offset:60416
	s_waitcnt lgkmcnt(4)
	v_mfma_f32_32x32x16_bf16 v[112:127], v[190:193], v[168:171], v[112:127]
	ds_read_b128 v[244:247], v206 offset:62464
	s_waitcnt lgkmcnt(4)
	v_mfma_f32_32x32x16_bf16 v[112:127], v[194:197], v[164:167], v[112:127]
	ds_read_b128 v[190:193], v206 offset:64512
	s_waitcnt lgkmcnt(4)
	v_mfma_f32_32x32x16_bf16 v[112:127], v[252:255], v[160:163], v[112:127]
	ds_read_b64_tr_b16 v[194:195], v201 offset:32768
	ds_read_b64_tr_b16 v[196:197], v201 offset:34816
	s_waitcnt lgkmcnt(5)
	v_mfma_f32_32x32x16_bf16 v[112:127], v[236:239], v[156:159], v[112:127]
	ds_read_b64_tr_b16 v[252:253], v201 offset:36864
	ds_read_b64_tr_b16 v[254:255], v201 offset:38912
	s_waitcnt lgkmcnt(6)
	v_mfma_f32_32x32x16_bf16 v[112:127], v[240:243], v[152:155], v[112:127]
	ds_read_b64_tr_b16 v[236:237], v201 offset:40960
	ds_read_b64_tr_b16 v[238:239], v201 offset:43008
	s_waitcnt lgkmcnt(7)
	v_mfma_f32_32x32x16_bf16 v[112:127], v[244:247], v[148:151], v[112:127]
	ds_read_b64_tr_b16 v[240:241], v201 offset:45056
	ds_read_b64_tr_b16 v[242:243], v201 offset:47104
	s_waitcnt lgkmcnt(8)
	v_mfma_f32_32x32x16_bf16 v[112:127], v[190:193], v[144:147], v[112:127]
	ds_read_b64_tr_b16 v[244:245], v201 offset:33280
	ds_read_b64_tr_b16 v[246:247], v201 offset:35328
	s_waitcnt lgkmcnt(8)
	v_mfma_f32_32x32x16_bf16 v[80:95], v[220:223], v[194:197], v[80:95]
	ds_read_b64_tr_b16 v[190:191], v201 offset:37376
	ds_read_b64_tr_b16 v[192:193], v201 offset:39424
	s_waitcnt lgkmcnt(8)
	v_mfma_f32_32x32x16_bf16 v[80:95], v[224:227], v[252:255], v[80:95]
	ds_read_b64_tr_b16 v[194:195], v201 offset:41472
	ds_read_b64_tr_b16 v[196:197], v201 offset:43520
	s_waitcnt lgkmcnt(8)
	v_mfma_f32_32x32x16_bf16 v[80:95], v[228:231], v[236:239], v[80:95]
	ds_read_b64_tr_b16 v[252:253], v201 offset:45568
	ds_read_b64_tr_b16 v[254:255], v201 offset:47616
	s_waitcnt lgkmcnt(8)
	v_mfma_f32_32x32x16_bf16 v[80:95], v[232:235], v[240:243], v[80:95]
	ds_read_b64_tr_b16 v[236:237], v201 offset:33792
	ds_read_b64_tr_b16 v[238:239], v201 offset:35840
	s_waitcnt lgkmcnt(8)
	v_mfma_f32_32x32x16_bf16 v[64:79], v[220:223], v[244:247], v[64:79]
	ds_read_b64_tr_b16 v[240:241], v201 offset:37888
	ds_read_b64_tr_b16 v[242:243], v201 offset:39936
	s_waitcnt lgkmcnt(8)
	v_mfma_f32_32x32x16_bf16 v[64:79], v[224:227], v[190:193], v[64:79]
	ds_read_b64_tr_b16 v[244:245], v201 offset:41984
	ds_read_b64_tr_b16 v[246:247], v201 offset:44032
	s_waitcnt lgkmcnt(8)
	v_mfma_f32_32x32x16_bf16 v[64:79], v[228:231], v[194:197], v[64:79]
	ds_read_b64_tr_b16 v[190:191], v201 offset:46080
	ds_read_b64_tr_b16 v[192:193], v201 offset:48128
	s_waitcnt lgkmcnt(8)
	v_mfma_f32_32x32x16_bf16 v[64:79], v[232:235], v[252:255], v[64:79]
	ds_read_b64_tr_b16 v[194:195], v201 offset:34304
	ds_read_b64_tr_b16 v[196:197], v201 offset:36352
	s_waitcnt lgkmcnt(8)
	v_mfma_f32_32x32x16_bf16 v[48:63], v[220:223], v[236:239], v[48:63]
	ds_read_b64_tr_b16 v[252:253], v201 offset:38400
	ds_read_b64_tr_b16 v[254:255], v201 offset:40448
	s_waitcnt lgkmcnt(8)
	v_mfma_f32_32x32x16_bf16 v[48:63], v[224:227], v[240:243], v[48:63]
	ds_read_b64_tr_b16 v[236:237], v201 offset:42496
	ds_read_b64_tr_b16 v[238:239], v201 offset:44544
	s_waitcnt lgkmcnt(8)
	v_mfma_f32_32x32x16_bf16 v[48:63], v[228:231], v[244:247], v[48:63]
	ds_read_b64_tr_b16 v[240:241], v201 offset:46592
	ds_read_b64_tr_b16 v[242:243], v201 offset:48640
	s_waitcnt lgkmcnt(8)
	v_mfma_f32_32x32x16_bf16 v[48:63], v[232:235], v[190:193], v[48:63]
	s_waitcnt lgkmcnt(6)
	v_mfma_f32_32x32x16_bf16 v[32:47], v[220:223], v[194:197], v[32:47]
	s_waitcnt lgkmcnt(4)
	v_mfma_f32_32x32x16_bf16 v[32:47], v[224:227], v[252:255], v[32:47]
	s_waitcnt lgkmcnt(2)
	v_mfma_f32_32x32x16_bf16 v[32:47], v[228:231], v[236:239], v[32:47]
	s_waitcnt lgkmcnt(0)
	v_mfma_f32_32x32x16_bf16 v[32:47], v[232:235], v[240:243], v[32:47]
	s_setprio 0
	s_waitcnt vmcnt(0) lgkmcnt(0)
	s_barrier
	ds_read_b64_tr_b16 v[236:237], v201 offset:49152
	ds_read_b64_tr_b16 v[238:239], v201 offset:51200
	ds_read_b64_tr_b16 v[240:241], v201 offset:53248
	ds_read_b64_tr_b16 v[242:243], v201 offset:55296
	ds_read_b64_tr_b16 v[244:245], v201 offset:57344
	ds_read_b64_tr_b16 v[246:247], v201 offset:59392
	ds_read_b64_tr_b16 v[190:191], v201 offset:61440
	ds_read_b64_tr_b16 v[192:193], v201 offset:63488
	ds_read_b64_tr_b16 v[194:195], v201 offset:49664
	ds_read_b64_tr_b16 v[196:197], v201 offset:51712
	v_exp_f32_e32 v96, v96
	v_exp_f32_e32 v97, v97
	v_exp_f32_e32 v98, v98
	v_exp_f32_e32 v99, v99
	v_exp_f32_e32 v100, v100
	v_exp_f32_e32 v101, v101
	v_exp_f32_e32 v102, v102
	v_exp_f32_e32 v103, v103
	v_exp_f32_e32 v104, v104
	v_exp_f32_e32 v105, v105
	v_exp_f32_e32 v106, v106
	v_exp_f32_e32 v107, v107
	v_exp_f32_e32 v108, v108
	v_exp_f32_e32 v109, v109
	v_exp_f32_e32 v110, v110
	v_exp_f32_e32 v111, v111
	v_exp_f32_e32 v112, v112
	v_exp_f32_e32 v113, v113
	v_exp_f32_e32 v114, v114
	v_exp_f32_e32 v115, v115
	v_exp_f32_e32 v116, v116
	v_exp_f32_e32 v117, v117
	v_exp_f32_e32 v118, v118
	v_exp_f32_e32 v119, v119
	v_exp_f32_e32 v120, v120
	v_exp_f32_e32 v121, v121
	v_exp_f32_e32 v122, v122
	v_exp_f32_e32 v123, v123
	v_exp_f32_e32 v124, v124
	v_exp_f32_e32 v125, v125
	v_exp_f32_e32 v126, v126
	v_exp_f32_e32 v127, v127
	v_cvt_pk_bf16_f32 v220, v96, v97
	v_cvt_pk_bf16_f32 v221, v98, v99
	v_cvt_pk_bf16_f32 v222, v100, v101
	v_cvt_pk_bf16_f32 v223, v102, v103
	v_add_f32_e32 v218, v96, v218
	v_add_f32_e32 v248, v97, v248
	v_add_f32_e32 v218, v98, v218
	v_add_f32_e32 v248, v99, v248
	v_add_f32_e32 v218, v100, v218
	v_add_f32_e32 v248, v101, v248
	v_add_f32_e32 v218, v102, v218
	v_add_f32_e32 v248, v103, v248
	v_cvt_pk_bf16_f32 v224, v104, v105
	v_cvt_pk_bf16_f32 v225, v106, v107
	v_cvt_pk_bf16_f32 v226, v108, v109
	v_cvt_pk_bf16_f32 v227, v110, v111
	v_add_f32_e32 v218, v104, v218
	v_add_f32_e32 v248, v105, v248
	v_add_f32_e32 v218, v106, v218
	v_add_f32_e32 v248, v107, v248
	v_add_f32_e32 v218, v108, v218
	v_add_f32_e32 v248, v109, v248
	v_add_f32_e32 v218, v110, v218
	v_add_f32_e32 v248, v111, v248
	v_cvt_pk_bf16_f32 v228, v112, v113
	v_cvt_pk_bf16_f32 v229, v114, v115
	v_cvt_pk_bf16_f32 v230, v116, v117
	v_cvt_pk_bf16_f32 v231, v118, v119
	v_add_f32_e32 v249, v112, v249
	v_add_f32_e32 v251, v113, v251
	v_add_f32_e32 v249, v114, v249
	v_add_f32_e32 v251, v115, v251
	v_add_f32_e32 v249, v116, v249
	v_add_f32_e32 v251, v117, v251
	v_add_f32_e32 v249, v118, v249
	v_add_f32_e32 v251, v119, v251
	v_cvt_pk_bf16_f32 v232, v120, v121
	v_cvt_pk_bf16_f32 v233, v122, v123
	v_cvt_pk_bf16_f32 v234, v124, v125
	v_cvt_pk_bf16_f32 v235, v126, v127
	v_add_f32_e32 v249, v120, v249
	v_add_f32_e32 v251, v121, v251
	v_add_f32_e32 v249, v122, v249
	v_add_f32_e32 v251, v123, v251
	v_add_f32_e32 v249, v124, v249
	v_add_f32_e32 v251, v125, v251
	v_add_f32_e32 v249, v126, v249
	v_add_f32_e32 v251, v127, v251
	s_waitcnt vmcnt(0)
	s_barrier
	s_setprio 1
	s_waitcnt lgkmcnt(8)
	v_mfma_f32_32x32x16_bf16 v[80:95], v[220:223], v[236:239], v[80:95]
	ds_read_b64_tr_b16 v[252:253], v201 offset:53760
	ds_read_b64_tr_b16 v[254:255], v201 offset:55808
	s_waitcnt lgkmcnt(8)
	v_mfma_f32_32x32x16_bf16 v[80:95], v[224:227], v[240:243], v[80:95]
	ds_read_b64_tr_b16 v[236:237], v201 offset:57856
	ds_read_b64_tr_b16 v[238:239], v201 offset:59904
	s_waitcnt lgkmcnt(8)
	v_mfma_f32_32x32x16_bf16 v[80:95], v[228:231], v[244:247], v[80:95]
	ds_read_b64_tr_b16 v[240:241], v201 offset:61952
	ds_read_b64_tr_b16 v[242:243], v201 offset:64000
	s_waitcnt lgkmcnt(8)
	v_mfma_f32_32x32x16_bf16 v[80:95], v[232:235], v[190:193], v[80:95]
	ds_read_b64_tr_b16 v[244:245], v201 offset:50176
	ds_read_b64_tr_b16 v[246:247], v201 offset:52224
	s_waitcnt lgkmcnt(8)
	v_mfma_f32_32x32x16_bf16 v[64:79], v[220:223], v[194:197], v[64:79]
	ds_read_b64_tr_b16 v[190:191], v201 offset:54272
	ds_read_b64_tr_b16 v[192:193], v201 offset:56320
	s_waitcnt lgkmcnt(8)
	v_mfma_f32_32x32x16_bf16 v[64:79], v[224:227], v[252:255], v[64:79]
	ds_read_b64_tr_b16 v[194:195], v201 offset:58368
	ds_read_b64_tr_b16 v[196:197], v201 offset:60416
	s_waitcnt lgkmcnt(8)
	v_mfma_f32_32x32x16_bf16 v[64:79], v[228:231], v[236:239], v[64:79]
	ds_read_b64_tr_b16 v[252:253], v201 offset:62464
	ds_read_b64_tr_b16 v[254:255], v201 offset:64512
	s_waitcnt lgkmcnt(8)
	v_mfma_f32_32x32x16_bf16 v[64:79], v[232:235], v[240:243], v[64:79]
	ds_read_b64_tr_b16 v[236:237], v201 offset:50688
	ds_read_b64_tr_b16 v[238:239], v201 offset:52736
	s_waitcnt lgkmcnt(8)
	v_mfma_f32_32x32x16_bf16 v[48:63], v[220:223], v[244:247], v[48:63]
	ds_read_b64_tr_b16 v[240:241], v201 offset:54784
	ds_read_b64_tr_b16 v[242:243], v201 offset:56832
	s_waitcnt lgkmcnt(8)
	v_mfma_f32_32x32x16_bf16 v[48:63], v[224:227], v[190:193], v[48:63]
	ds_read_b64_tr_b16 v[244:245], v201 offset:58880
	ds_read_b64_tr_b16 v[246:247], v201 offset:60928
	s_waitcnt lgkmcnt(8)
	v_mfma_f32_32x32x16_bf16 v[48:63], v[228:231], v[194:197], v[48:63]
	ds_read_b64_tr_b16 v[190:191], v201 offset:62976
	ds_read_b64_tr_b16 v[192:193], v201 offset:65024
	s_waitcnt lgkmcnt(8)
	v_mfma_f32_32x32x16_bf16 v[48:63], v[232:235], v[252:255], v[48:63]
	s_waitcnt lgkmcnt(6)
	v_mfma_f32_32x32x16_bf16 v[32:47], v[220:223], v[236:239], v[32:47]
	s_waitcnt lgkmcnt(4)
	v_mfma_f32_32x32x16_bf16 v[32:47], v[224:227], v[240:243], v[32:47]
	s_waitcnt lgkmcnt(2)
	v_mfma_f32_32x32x16_bf16 v[32:47], v[228:231], v[244:247], v[32:47]
	s_waitcnt lgkmcnt(0)
	v_mfma_f32_32x32x16_bf16 v[32:47], v[232:235], v[190:193], v[32:47]
	s_setprio 0
	s_waitcnt vmcnt(0) lgkmcnt(0)
	s_barrier
	s_cmp_gt_u32 s33, 3
	s_cbranch_scc1 .Lattn_lag_out
	s_barrier
.Lattn_lag_out:
	v_add_f32_e32 v218, v218, v248
	v_add_f32_e32 v249, v249, v251
	s_and_b32 s0, s97, 0x3fffffc0
	s_lshl_b32 s0, s0, 2
	v_add_f32_e32 v236, v218, v249
	s_add_i32 s33, s0, 0x20010
	v_mov_b32_e32 v237, v236
	v_lshl_add_u32 v240, v178, 2, s33
	s_nop 1
	v_permlane32_swap_b32_e32 v236, v237
	v_mov_b32_e32 v0, 0
	v_mov_b32_e32 v1, 0
	v_mov_b32_e32 v2, 0
	v_mov_b32_e32 v3, 0
	v_mov_b32_e32 v4, 0
	v_mov_b32_e32 v5, 0
	v_mov_b32_e32 v6, 0
	v_mov_b32_e32 v7, 0
	v_mov_b32_e32 v8, 0
	v_mov_b32_e32 v9, 0
	v_mov_b32_e32 v10, 0
	v_mov_b32_e32 v11, 0
	v_mov_b32_e32 v12, 0
	v_mov_b32_e32 v13, 0
	v_mov_b32_e32 v14, 0
	v_mov_b32_e32 v15, 0
	v_add_f32_e32 v236, v236, v237
	s_and_saveexec_b64 s[0:1], vcc
	ds_write_b32 v240, v236
	s_branch .LBB0_236
